# GEMM K-loops: MFMA issue order within each 16-block changed so 4 consecutive MFMAs share srcA (operand-reuse/power experiment), on top of v009
# baseline (speedup 1.0000x reference)
; #define PG8_STAGE(bufoff, gbase, voff) do { _Pragma("unroll") for (int _i = 0; _i < 2; ++_i) \
;         __builtin_amdgcn_global_load_lds((const unsigned*)((const char*)(gbase) + (voff)[_i]), (LAS unsigned*)(lds + (bufoff) + ldsw + _i * 8192), 16, 0, 0); } while (0)
; #define PG8_LDA(dst, b, h) do { _Pragma("unroll") for (int m = 0; m < 4; ++m) _Pragma("unroll") for (int k = 0; k < 2; ++k) dst[m][k] = *(const LAS bf16x8*)(lds + PG8_SA(b, h) + aoff + m * 2048 + k * 1024); } while (0)
; #define PG8_LDB(dst, b, h) do { _Pragma("unroll") for (int n = 0; n < 2; ++n) _Pragma("unroll") for (int k = 0; k < 2; ++k) dst[n][k] = *(const LAS bf16x8*)(lds + PG8_SB(b, h) + boff + n * 2048 + k * 1024); } while (0)
; #define PG8_WAIT_V(n) asm volatile("s_waitcnt vmcnt(" #n ")" ::: "memory")
; #define PG8_WAIT_L(n) asm volatile("s_waitcnt lgkmcnt(" #n ")" ::: "memory")
; #define PG8_BAR __builtin_amdgcn_s_barrier()
; #define PG8_SCHED __builtin_amdgcn_sched_barrier(0)
; template <class Epi, class Sched, bool I8 = false>
; __device__ __forceinline__ void gemm_phase(LAS unsigned char* lds, const Gemm g, const Sched& S, const Epi& E) {
;     ...
;         for (int t = 0; t < nt; t += 2) {
;             const bool last = (t == nt - 2);
;             const char* a1 = cA + (size_t)(t + 1) * kstep;
;             const char* a2 = last ? nA : cA + (size_t)(t + 2) * kstep; const char* b2 = last ? nB : cB + (size_t)(t + 2) * kstep;
;             const char* a3 = a2 + kstep; const char* b3 = b2 + kstep;
;             PG8_LDB(B0, 0, 0); PG8_LDB(B1, 0, 1); PG8_SCHED; PG8_LDA(At, 0, 0); PG8_STAGE(PG8_SA(1, 1), a1 + hstepA, voffA);
;             PG8_WAIT_V(8); PG8_WAIT_L(0); PG8_BAR; PG8_MMA(0, 0, At, B0); PG8_MMA(0, 1, At, B1); PG8_BAR; PG8_SCHED;
;             PG8_LDA(At, 0, 1); PG8_STAGE(PG8_SB(0, 0), b2, voffB); PG8_STAGE(PG8_SB(0, 1), b2 + hstepB, voffB); PG8_STAGE(PG8_SA(0, 0), a2, voffA);
;             PG8_WAIT_V(8); PG8_WAIT_L(0); PG8_BAR; PG8_MMA(1, 0, At, B0); PG8_MMA(1, 1, At, B1); PG8_BAR; PG8_SCHED;
.LBB0_1169:
	ds_read_b128 v[90:93], v169
	ds_read_b128 v[98:101], v169 offset:1024
	ds_read_b128 v[172:175], v169 offset:2048
	ds_read_b128 v[176:179], v169 offset:3072
	ds_read_b128 v[180:183], v170
	ds_read_b128 v[184:187], v170 offset:1024
	ds_read_b128 v[188:191], v170 offset:2048
	ds_read_b128 v[192:195], v170 offset:3072
	s_add_u32 s22, s20, 0x4000
	s_addc_u32 s23, s21, 0
	s_cmp_eq_u32 s53, 28
	s_cselect_b32 s26, s49, s22
	s_cselect_b32 s27, s13, s23
	s_cselect_b32 s24, s50, s51
	s_cselect_b32 s25, s11, s52
	s_add_u32 s22, s26, 0x8000
	s_addc_u32 s23, s27, 0
	s_sub_u32 s98, s20, 0x4000
	s_subb_u32 s99, s21, 0
	s_mov_b32 m0, s43
	s_nop 0
	global_load_lds_dwordx4 v144, s[98:99]
	s_mov_b32 m0, s44
	s_nop 0
	global_load_lds_dwordx4 v140, s[98:99]
	s_add_i32 m0, s36, 0xc000
	ds_read_b128 v[196:199], v171
	ds_read_b128 v[200:203], v171 offset:1024
	ds_read_b128 v[204:207], v171 offset:2048
	ds_read_b128 v[208:211], v171 offset:3072
	ds_read_b128 v[212:215], v171 offset:4096
	ds_read_b128 v[216:219], v171 offset:5120
	ds_read_b128 v[220:223], v171 offset:6144
	ds_read_b128 v[224:227], v171 offset:7168
	global_load_lds_dwordx4 v148, s[20:21]
	s_add_i32 m0, s36, 0xe000
	s_nop 0
	global_load_lds_dwordx4 v150, s[20:21]
	s_waitcnt vmcnt(8)
	s_waitcnt lgkmcnt(0)
	s_barrier
	s_setprio 1
	s_waitcnt lgkmcnt(0)
	v_mfma_i32_16x16x64_i8 v[134:137], v[90:93], v[196:199], v[134:137]
	v_mfma_i32_16x16x64_i8 v[118:121], v[90:93], v[204:207], v[118:121]
	v_mfma_i32_16x16x64_i8 v[102:105], v[90:93], v[212:215], v[102:105]
	v_mfma_i32_16x16x64_i8 v[78:81], v[90:93], v[220:223], v[78:81]
	v_mfma_i32_16x16x64_i8 v[130:133], v[172:175], v[196:199], v[130:133]
	v_mfma_i32_16x16x64_i8 v[114:117], v[172:175], v[204:207], v[114:117]
	v_mfma_i32_16x16x64_i8 v[94:97], v[172:175], v[212:215], v[94:97]
	v_mfma_i32_16x16x64_i8 v[74:77], v[172:175], v[220:223], v[74:77]
	v_mfma_i32_16x16x64_i8 v[134:137], v[98:101], v[200:203], v[134:137]
	v_mfma_i32_16x16x64_i8 v[118:121], v[98:101], v[208:211], v[118:121]
	v_mfma_i32_16x16x64_i8 v[102:105], v[98:101], v[216:219], v[102:105]
	v_mfma_i32_16x16x64_i8 v[78:81], v[98:101], v[224:227], v[78:81]
	v_mfma_i32_16x16x64_i8 v[130:133], v[176:179], v[200:203], v[130:133]
	v_mfma_i32_16x16x64_i8 v[114:117], v[176:179], v[208:211], v[114:117]
	v_mfma_i32_16x16x64_i8 v[94:97], v[176:179], v[216:219], v[94:97]
	v_mfma_i32_16x16x64_i8 v[74:77], v[176:179], v[224:227], v[74:77]
	s_setprio 0
	s_setprio 1
	v_mfma_i32_16x16x64_i8 v[126:129], v[180:183], v[196:199], v[126:129]
	v_mfma_i32_16x16x64_i8 v[110:113], v[180:183], v[204:207], v[110:113]
	v_mfma_i32_16x16x64_i8 v[86:89], v[180:183], v[212:215], v[86:89]
	v_mfma_i32_16x16x64_i8 v[70:73], v[180:183], v[220:223], v[70:73]
	v_mfma_i32_16x16x64_i8 v[122:125], v[188:191], v[196:199], v[122:125]
	v_mfma_i32_16x16x64_i8 v[106:109], v[188:191], v[204:207], v[106:109]
	v_mfma_i32_16x16x64_i8 v[82:85], v[188:191], v[212:215], v[82:85]
	v_mfma_i32_16x16x64_i8 v[66:69], v[188:191], v[220:223], v[66:69]
	v_mfma_i32_16x16x64_i8 v[126:129], v[184:187], v[200:203], v[126:129]
	v_mfma_i32_16x16x64_i8 v[110:113], v[184:187], v[208:211], v[110:113]
	v_mfma_i32_16x16x64_i8 v[86:89], v[184:187], v[216:219], v[86:89]
	v_mfma_i32_16x16x64_i8 v[70:73], v[184:187], v[224:227], v[70:73]
	v_mfma_i32_16x16x64_i8 v[122:125], v[192:195], v[200:203], v[122:125]
	v_mfma_i32_16x16x64_i8 v[106:109], v[192:195], v[208:211], v[106:109]
	v_mfma_i32_16x16x64_i8 v[82:85], v[192:195], v[216:219], v[82:85]
	v_mfma_i32_16x16x64_i8 v[66:69], v[192:195], v[224:227], v[66:69]
	s_setprio 0
	s_barrier
	s_add_i32 s54, s46, s33
	s_mov_b32 m0, s54
	ds_read_b128 v[196:199], v171 offset:16384
	ds_read_b128 v[200:203], v171 offset:17408
	ds_read_b128 v[204:207], v171 offset:18432
	ds_read_b128 v[208:211], v171 offset:19456
	ds_read_b128 v[212:215], v171 offset:20480
	ds_read_b128 v[216:219], v171 offset:21504
	ds_read_b128 v[220:223], v171 offset:22528
	ds_read_b128 v[224:227], v171 offset:23552
	global_load_lds_dwordx4 v142, s[24:25]
	s_add_i32 m0, s54, 0x2000
	s_add_u32 s54, s24, 0x4000
	s_addc_u32 s55, s25, 0
	s_add_i32 s56, s47, s33
	global_load_lds_dwordx4 v138, s[24:25]
	s_mov_b32 m0, s56
	s_nop 0
	global_load_lds_dwordx4 v142, s[54:55]
	s_add_i32 m0, s56, 0x2000
	s_nop 0
	global_load_lds_dwordx4 v138, s[54:55]
	s_waitcnt vmcnt(6)
	s_waitcnt lgkmcnt(0)
	s_barrier
	s_setprio 1
	s_waitcnt lgkmcnt(0)
	v_mfma_i32_16x16x64_i8 v[62:65], v[90:93], v[196:199], v[62:65]
	v_mfma_i32_16x16x64_i8 v[46:49], v[90:93], v[204:207], v[46:49]
	v_mfma_i32_16x16x64_i8 v[30:33], v[90:93], v[212:215], v[30:33]
	v_mfma_i32_16x16x64_i8 v[14:17], v[90:93], v[220:223], v[14:17]
	v_mfma_i32_16x16x64_i8 v[58:61], v[172:175], v[196:199], v[58:61]
	v_mfma_i32_16x16x64_i8 v[42:45], v[172:175], v[204:207], v[42:45]
	v_mfma_i32_16x16x64_i8 v[26:29], v[172:175], v[212:215], v[26:29]
	v_mfma_i32_16x16x64_i8 v[10:13], v[172:175], v[220:223], v[10:13]
	v_mfma_i32_16x16x64_i8 v[62:65], v[98:101], v[200:203], v[62:65]
	v_mfma_i32_16x16x64_i8 v[46:49], v[98:101], v[208:211], v[46:49]
	v_mfma_i32_16x16x64_i8 v[30:33], v[98:101], v[216:219], v[30:33]
	v_mfma_i32_16x16x64_i8 v[14:17], v[98:101], v[224:227], v[14:17]
	v_mfma_i32_16x16x64_i8 v[58:61], v[176:179], v[200:203], v[58:61]
	v_mfma_i32_16x16x64_i8 v[42:45], v[176:179], v[208:211], v[42:45]
	v_mfma_i32_16x16x64_i8 v[26:29], v[176:179], v[216:219], v[26:29]
	v_mfma_i32_16x16x64_i8 v[10:13], v[176:179], v[224:227], v[10:13]
	s_setprio 0
	s_setprio 1
	v_mfma_i32_16x16x64_i8 v[54:57], v[180:183], v[196:199], v[54:57]
	v_mfma_i32_16x16x64_i8 v[38:41], v[180:183], v[204:207], v[38:41]
	v_mfma_i32_16x16x64_i8 v[22:25], v[180:183], v[212:215], v[22:25]
	v_mfma_i32_16x16x64_i8 v[6:9], v[180:183], v[220:223], v[6:9]
	v_mfma_i32_16x16x64_i8 v[50:53], v[188:191], v[196:199], v[50:53]
	v_mfma_i32_16x16x64_i8 v[34:37], v[188:191], v[204:207], v[34:37]
	v_mfma_i32_16x16x64_i8 v[18:21], v[188:191], v[212:215], v[18:21]
	v_mfma_i32_16x16x64_i8 v[2:5], v[188:191], v[220:223], v[2:5]
	v_mfma_i32_16x16x64_i8 v[54:57], v[184:187], v[200:203], v[54:57]
	v_mfma_i32_16x16x64_i8 v[38:41], v[184:187], v[208:211], v[38:41]
	v_mfma_i32_16x16x64_i8 v[22:25], v[184:187], v[216:219], v[22:25]
	v_mfma_i32_16x16x64_i8 v[6:9], v[184:187], v[224:227], v[6:9]
	v_mfma_i32_16x16x64_i8 v[50:53], v[192:195], v[200:203], v[50:53]
	v_mfma_i32_16x16x64_i8 v[34:37], v[192:195], v[208:211], v[34:37]
	v_mfma_i32_16x16x64_i8 v[18:21], v[192:195], v[216:219], v[18:21]
	v_mfma_i32_16x16x64_i8 v[2:5], v[192:195], v[224:227], v[2:5]
	s_setprio 0
	s_barrier
; #define PG8_STAGE(bufoff, gbase, voff) do { _Pragma("unroll") for (int _i = 0; _i < 2; ++_i) \
;         __builtin_amdgcn_global_load_lds((const unsigned*)((const char*)(gbase) + (voff)[_i]), (LAS unsigned*)(lds + (bufoff) + ldsw + _i * 8192), 16, 0, 0); } while (0)
; #define PG8_LDA(dst, b, h) do { _Pragma("unroll") for (int m = 0; m < 4; ++m) _Pragma("unroll") for (int k = 0; k < 2; ++k) dst[m][k] = *(const LAS bf16x8*)(lds + PG8_SA(b, h) + aoff + m * 2048 + k * 1024); } while (0)
; #define PG8_LDB(dst, b, h) do { _Pragma("unroll") for (int n = 0; n < 2; ++n) _Pragma("unroll") for (int k = 0; k < 2; ++k) dst[n][k] = *(const LAS bf16x8*)(lds + PG8_SB(b, h) + boff + n * 2048 + k * 1024); } while (0)
; #define PG8_WAIT_V(n) asm volatile("s_waitcnt vmcnt(" #n ")" ::: "memory")
; #define PG8_WAIT_L(n) asm volatile("s_waitcnt lgkmcnt(" #n ")" ::: "memory")
; #define PG8_BAR __builtin_amdgcn_s_barrier()
; #define PG8_SCHED __builtin_amdgcn_sched_barrier(0)
; template <class Epi, class Sched, bool I8 = false>
; __device__ __forceinline__ void gemm_phase(LAS unsigned char* lds, const Gemm g, const Sched& S, const Epi& E) {
;     ...
;             PG8_LDB(B0, 1, 0); PG8_LDB(B1, 1, 1); PG8_SCHED; PG8_LDA(At, 1, 0); PG8_STAGE(PG8_SA(0, 1), a2 + hstepA, voffA);
;             PG8_WAIT_V(8); PG8_WAIT_L(0); PG8_BAR; PG8_MMA(0, 0, At, B0); PG8_MMA(0, 1, At, B1); PG8_BAR; PG8_SCHED;
;             PG8_LDA(At, 1, 1); PG8_STAGE(PG8_SB(1, 0), b3, voffB); PG8_STAGE(PG8_SB(1, 1), b3 + hstepB, voffB); PG8_STAGE(PG8_SA(1, 0), a3, voffA);
;             PG8_WAIT_V(8); PG8_WAIT_L(0); PG8_BAR; PG8_MMA(1, 0, At, B0); PG8_MMA(1, 1, At, B1); PG8_BAR; PG8_SCHED;
;         }
	s_add_i32 s54, 0, 0x18000
	v_add_u32_e32 v146, s54, v165
	s_add_i32 s55, 0, 0x1c000
	ds_read_b128 v[90:93], v146
	ds_read_b128 v[98:101], v146 offset:1024
	ds_read_b128 v[172:175], v146 offset:2048
	ds_read_b128 v[176:179], v146 offset:3072
	v_add_u32_e32 v146, s55, v165
	ds_read_b128 v[180:183], v146
	ds_read_b128 v[184:187], v146 offset:1024
	ds_read_b128 v[188:191], v146 offset:2048
	ds_read_b128 v[192:195], v146 offset:3072
	s_mov_b32 m0, s36
	s_nop 0
	global_load_lds_dwordx4 v144, s[26:27]
	s_mov_b32 m0, s37
	s_nop 0
	global_load_lds_dwordx4 v140, s[26:27]
	s_add_u32 s26, s26, 0x4000
	s_addc_u32 s27, s27, 0
	s_mov_b32 m0, s38
	ds_read_b128 v[196:199], v171 offset:32768
	ds_read_b128 v[200:203], v171 offset:33792
	ds_read_b128 v[204:207], v171 offset:34816
	ds_read_b128 v[208:211], v171 offset:35840
	ds_read_b128 v[212:215], v171 offset:36864
	ds_read_b128 v[216:219], v171 offset:37888
	ds_read_b128 v[220:223], v171 offset:38912
	ds_read_b128 v[224:227], v171 offset:39936
	global_load_lds_dwordx4 v144, s[26:27]
	s_mov_b32 m0, s39
	s_nop 0
	global_load_lds_dwordx4 v140, s[26:27]
	s_waitcnt vmcnt(8)
	s_waitcnt lgkmcnt(0)
	s_barrier
	s_setprio 1
	s_waitcnt lgkmcnt(0)
	v_mfma_i32_16x16x64_i8 v[134:137], v[90:93], v[196:199], v[134:137]
	v_mfma_i32_16x16x64_i8 v[118:121], v[90:93], v[204:207], v[118:121]
	v_mfma_i32_16x16x64_i8 v[102:105], v[90:93], v[212:215], v[102:105]
	v_mfma_i32_16x16x64_i8 v[78:81], v[90:93], v[220:223], v[78:81]
	v_mfma_i32_16x16x64_i8 v[130:133], v[172:175], v[196:199], v[130:133]
	v_mfma_i32_16x16x64_i8 v[114:117], v[172:175], v[204:207], v[114:117]
	v_mfma_i32_16x16x64_i8 v[94:97], v[172:175], v[212:215], v[94:97]
	v_mfma_i32_16x16x64_i8 v[74:77], v[172:175], v[220:223], v[74:77]
	v_mfma_i32_16x16x64_i8 v[134:137], v[98:101], v[200:203], v[134:137]
	v_mfma_i32_16x16x64_i8 v[118:121], v[98:101], v[208:211], v[118:121]
	v_mfma_i32_16x16x64_i8 v[102:105], v[98:101], v[216:219], v[102:105]
	v_mfma_i32_16x16x64_i8 v[78:81], v[98:101], v[224:227], v[78:81]
	v_mfma_i32_16x16x64_i8 v[130:133], v[176:179], v[200:203], v[130:133]
	v_mfma_i32_16x16x64_i8 v[114:117], v[176:179], v[208:211], v[114:117]
	v_mfma_i32_16x16x64_i8 v[94:97], v[176:179], v[216:219], v[94:97]
	v_mfma_i32_16x16x64_i8 v[74:77], v[176:179], v[224:227], v[74:77]
	s_setprio 0
	s_setprio 1
	v_mfma_i32_16x16x64_i8 v[126:129], v[180:183], v[196:199], v[126:129]
	v_mfma_i32_16x16x64_i8 v[110:113], v[180:183], v[204:207], v[110:113]
	v_mfma_i32_16x16x64_i8 v[86:89], v[180:183], v[212:215], v[86:89]
	v_mfma_i32_16x16x64_i8 v[70:73], v[180:183], v[220:223], v[70:73]
	v_mfma_i32_16x16x64_i8 v[122:125], v[188:191], v[196:199], v[122:125]
	v_mfma_i32_16x16x64_i8 v[106:109], v[188:191], v[204:207], v[106:109]
	v_mfma_i32_16x16x64_i8 v[82:85], v[188:191], v[212:215], v[82:85]
	v_mfma_i32_16x16x64_i8 v[66:69], v[188:191], v[220:223], v[66:69]
	v_mfma_i32_16x16x64_i8 v[126:129], v[184:187], v[200:203], v[126:129]
	v_mfma_i32_16x16x64_i8 v[110:113], v[184:187], v[208:211], v[110:113]
	v_mfma_i32_16x16x64_i8 v[86:89], v[184:187], v[216:219], v[86:89]
	v_mfma_i32_16x16x64_i8 v[70:73], v[184:187], v[224:227], v[70:73]
	v_mfma_i32_16x16x64_i8 v[122:125], v[192:195], v[200:203], v[122:125]
	v_mfma_i32_16x16x64_i8 v[106:109], v[192:195], v[208:211], v[106:109]
	v_mfma_i32_16x16x64_i8 v[82:85], v[192:195], v[216:219], v[82:85]
	v_mfma_i32_16x16x64_i8 v[66:69], v[192:195], v[224:227], v[66:69]
	s_setprio 0
	s_barrier
	s_add_u32 s26, s24, 0x8000
	s_addc_u32 s27, s25, 0
	s_add_i32 s54, s54, s33
	s_mov_b32 m0, s54
	ds_read_b128 v[196:199], v171 offset:49152
	ds_read_b128 v[200:203], v171 offset:50176
	ds_read_b128 v[204:207], v171 offset:51200
	ds_read_b128 v[208:211], v171 offset:52224
	ds_read_b128 v[212:215], v171 offset:53248
	ds_read_b128 v[216:219], v171 offset:54272
	ds_read_b128 v[220:223], v171 offset:55296
	ds_read_b128 v[224:227], v171 offset:56320
	global_load_lds_dwordx4 v142, s[26:27]
	s_add_i32 m0, s54, 0x2000
	s_add_u32 s24, s24, 0xc000
	v_lshl_add_u64 v[158:159], s[26:27], 0, v[138:139]
	s_addc_u32 s25, s25, 0
	s_add_i32 s26, s55, s33
	global_load_lds_dwordx4 v[158:159], off
	s_mov_b32 m0, s26
	s_nop 0
	global_load_lds_dwordx4 v142, s[24:25]
	s_add_i32 m0, s26, 0x2000
	s_nop 0
	global_load_lds_dwordx4 v138, s[24:25]
	s_waitcnt vmcnt(6)
	s_waitcnt lgkmcnt(0)
	s_barrier
	s_setprio 1
	s_waitcnt lgkmcnt(0)
	v_mfma_i32_16x16x64_i8 v[62:65], v[90:93], v[196:199], v[62:65]
	v_mfma_i32_16x16x64_i8 v[46:49], v[90:93], v[204:207], v[46:49]
	v_mfma_i32_16x16x64_i8 v[30:33], v[90:93], v[212:215], v[30:33]
	v_mfma_i32_16x16x64_i8 v[14:17], v[90:93], v[220:223], v[14:17]
	v_mfma_i32_16x16x64_i8 v[58:61], v[172:175], v[196:199], v[58:61]
	v_mfma_i32_16x16x64_i8 v[42:45], v[172:175], v[204:207], v[42:45]
	v_mfma_i32_16x16x64_i8 v[26:29], v[172:175], v[212:215], v[26:29]
	v_mfma_i32_16x16x64_i8 v[10:13], v[172:175], v[220:223], v[10:13]
	v_mfma_i32_16x16x64_i8 v[62:65], v[98:101], v[200:203], v[62:65]
	v_mfma_i32_16x16x64_i8 v[46:49], v[98:101], v[208:211], v[46:49]
	v_mfma_i32_16x16x64_i8 v[30:33], v[98:101], v[216:219], v[30:33]
	v_mfma_i32_16x16x64_i8 v[14:17], v[98:101], v[224:227], v[14:17]
	v_mfma_i32_16x16x64_i8 v[58:61], v[176:179], v[200:203], v[58:61]
	v_mfma_i32_16x16x64_i8 v[42:45], v[176:179], v[208:211], v[42:45]
	v_mfma_i32_16x16x64_i8 v[26:29], v[176:179], v[216:219], v[26:29]
	v_mfma_i32_16x16x64_i8 v[10:13], v[176:179], v[224:227], v[10:13]
	s_setprio 0
	s_setprio 1
	v_mfma_i32_16x16x64_i8 v[54:57], v[180:183], v[196:199], v[54:57]
	v_mfma_i32_16x16x64_i8 v[38:41], v[180:183], v[204:207], v[38:41]
	v_mfma_i32_16x16x64_i8 v[22:25], v[180:183], v[212:215], v[22:25]
	v_mfma_i32_16x16x64_i8 v[6:9], v[180:183], v[220:223], v[6:9]
	v_mfma_i32_16x16x64_i8 v[50:53], v[188:191], v[196:199], v[50:53]
	v_mfma_i32_16x16x64_i8 v[34:37], v[188:191], v[204:207], v[34:37]
	v_mfma_i32_16x16x64_i8 v[18:21], v[188:191], v[212:215], v[18:21]
	v_mfma_i32_16x16x64_i8 v[2:5], v[188:191], v[220:223], v[2:5]
	v_mfma_i32_16x16x64_i8 v[54:57], v[184:187], v[200:203], v[54:57]
	v_mfma_i32_16x16x64_i8 v[38:41], v[184:187], v[208:211], v[38:41]
	v_mfma_i32_16x16x64_i8 v[22:25], v[184:187], v[216:219], v[22:25]
	v_mfma_i32_16x16x64_i8 v[6:9], v[184:187], v[224:227], v[6:9]
	v_mfma_i32_16x16x64_i8 v[50:53], v[192:195], v[200:203], v[50:53]
	v_mfma_i32_16x16x64_i8 v[34:37], v[192:195], v[208:211], v[34:37]
	v_mfma_i32_16x16x64_i8 v[18:21], v[192:195], v[216:219], v[18:21]
	v_mfma_i32_16x16x64_i8 v[2:5], v[192:195], v[224:227], v[2:5]
	s_setprio 0
	s_barrier
	s_add_i32 s53, s53, 2
	s_add_u32 s20, s20, 0x10000
	s_addc_u32 s21, s21, 0
	s_add_u32 s51, s51, 0x10000
	s_addc_u32 s52, s52, 0
	s_cmp_gt_u32 s53, 29
	s_cbranch_scc0 .LBB0_1169
	s_and_b64 vcc, exec, s[8:9]
	s_cbranch_vccz .LBB0_1172
	s_barrier

; #define PG8_STAGE(bufoff, gbase, voff) do { _Pragma("unroll") for (int _i = 0; _i < 2; ++_i) \
;         __builtin_amdgcn_global_load_lds((const unsigned*)((const char*)(gbase) + (voff)[_i]), (LAS unsigned*)(lds + (bufoff) + ldsw + _i * 8192), 16, 0, 0); } while (0)
; #define PG8_LDA(dst, b, h) do { _Pragma("unroll") for (int m = 0; m < 4; ++m) _Pragma("unroll") for (int k = 0; k < 2; ++k) dst[m][k] = *(const LAS bf16x8*)(lds + PG8_SA(b, h) + aoff + m * 2048 + k * 1024); } while (0)
; #define PG8_LDB(dst, b, h) do { _Pragma("unroll") for (int n = 0; n < 2; ++n) _Pragma("unroll") for (int k = 0; k < 2; ++k) dst[n][k] = *(const LAS bf16x8*)(lds + PG8_SB(b, h) + boff + n * 2048 + k * 1024); } while (0)
; #define PG8_WAIT_V(n) asm volatile("s_waitcnt vmcnt(" #n ")" ::: "memory")
; #define PG8_WAIT_L(n) asm volatile("s_waitcnt lgkmcnt(" #n ")" ::: "memory")
; #define PG8_BAR __builtin_amdgcn_s_barrier()
; #define PG8_SCHED __builtin_amdgcn_sched_barrier(0)
; template <class Epi, class Sched, bool I8 = false>
; __device__ __forceinline__ void gemm_phase(LAS unsigned char* lds, const Gemm g, const Sched& S, const Epi& E) {
;     ...
;         for (int t = 0; t < nt; t += 2) {
;             const bool last = (t == nt - 2);
;             const char* a1 = cA + (size_t)(t + 1) * kstep;
;             const char* a2 = last ? nA : cA + (size_t)(t + 2) * kstep; const char* b2 = last ? nB : cB + (size_t)(t + 2) * kstep;
;             const char* a3 = a2 + kstep; const char* b3 = b2 + kstep;
;             PG8_LDB(B0, 0, 0); PG8_LDB(B1, 0, 1); PG8_SCHED; PG8_LDA(At, 0, 0); PG8_STAGE(PG8_SA(1, 1), a1 + hstepA, voffA);
;             PG8_WAIT_V(8); PG8_WAIT_L(0); PG8_BAR; PG8_MMA(0, 0, At, B0); PG8_MMA(0, 1, At, B1); PG8_BAR; PG8_SCHED;
;             PG8_LDA(At, 0, 1); PG8_STAGE(PG8_SB(0, 0), b2, voffB); PG8_STAGE(PG8_SB(0, 1), b2 + hstepB, voffB); PG8_STAGE(PG8_SA(0, 0), a2, voffA);
;             PG8_WAIT_V(8); PG8_WAIT_L(0); PG8_BAR; PG8_MMA(1, 0, At, B0); PG8_MMA(1, 1, At, B1); PG8_BAR; PG8_SCHED;
.LBB0_1393:
	ds_read_b128 v[66:69], v180
	ds_read_b128 v[70:73], v180 offset:1024
	ds_read_b128 v[74:77], v180 offset:2048
	ds_read_b128 v[78:81], v180 offset:3072
	ds_read_b128 v[146:149], v181
	ds_read_b128 v[150:153], v181 offset:1024
	ds_read_b128 v[174:177], v181 offset:2048
	ds_read_b128 v[184:187], v181 offset:3072
	s_add_u32 s20, s18, 0x4000
	s_addc_u32 s21, s19, 0
	s_cmpk_eq_i32 s49, 0x52
	s_cselect_b32 s24, s0, s20
	s_cselect_b32 s25, s1, s21
	s_cselect_b32 s22, s16, s47
	s_cselect_b32 s23, s17, s48
	s_add_u32 s20, s24, 0x8000
	s_addc_u32 s21, s25, 0
	s_sub_u32 s98, s18, 0x4000
	s_subb_u32 s99, s19, 0
	s_mov_b32 m0, s37
	s_nop 0
	global_load_lds_dwordx4 v156, s[98:99]
	s_mov_b32 m0, s38
	s_nop 0
	global_load_lds_dwordx4 v160, s[98:99]
	s_add_i32 m0, s31, 0xc000
	ds_read_b128 v[188:191], v182
	ds_read_b128 v[192:195], v182 offset:1024
	ds_read_b128 v[196:199], v182 offset:2048
	ds_read_b128 v[200:203], v182 offset:3072
	ds_read_b128 v[204:207], v182 offset:4096
	ds_read_b128 v[208:211], v182 offset:5120
	ds_read_b128 v[212:215], v182 offset:6144
	ds_read_b128 v[216:219], v182 offset:7168
	global_load_lds_dwordx4 v166, s[18:19]
	s_add_i32 m0, s31, 0xe000
	s_nop 0
	global_load_lds_dwordx4 v168, s[18:19]
	s_waitcnt vmcnt(8)
	s_waitcnt lgkmcnt(0)
	s_barrier
	s_setprio 1
	s_waitcnt lgkmcnt(0)
	v_mfma_i32_16x16x64_i8 v[142:145], v[66:69], v[188:191], v[142:145]
	v_mfma_i32_16x16x64_i8 v[126:129], v[66:69], v[196:199], v[126:129]
	v_mfma_i32_16x16x64_i8 v[110:113], v[66:69], v[204:207], v[110:113]
	v_mfma_i32_16x16x64_i8 v[94:97], v[66:69], v[212:215], v[94:97]
	v_mfma_i32_16x16x64_i8 v[138:141], v[74:77], v[188:191], v[138:141]
	v_mfma_i32_16x16x64_i8 v[122:125], v[74:77], v[196:199], v[122:125]
	v_mfma_i32_16x16x64_i8 v[106:109], v[74:77], v[204:207], v[106:109]
	v_mfma_i32_16x16x64_i8 v[90:93], v[74:77], v[212:215], v[90:93]
	v_mfma_i32_16x16x64_i8 v[142:145], v[70:73], v[192:195], v[142:145]
	v_mfma_i32_16x16x64_i8 v[126:129], v[70:73], v[200:203], v[126:129]
	v_mfma_i32_16x16x64_i8 v[110:113], v[70:73], v[208:211], v[110:113]
	v_mfma_i32_16x16x64_i8 v[94:97], v[70:73], v[216:219], v[94:97]
	v_mfma_i32_16x16x64_i8 v[138:141], v[78:81], v[192:195], v[138:141]
	v_mfma_i32_16x16x64_i8 v[122:125], v[78:81], v[200:203], v[122:125]
	v_mfma_i32_16x16x64_i8 v[106:109], v[78:81], v[208:211], v[106:109]
	v_mfma_i32_16x16x64_i8 v[90:93], v[78:81], v[216:219], v[90:93]
	s_setprio 0
	s_setprio 1
	v_mfma_i32_16x16x64_i8 v[134:137], v[146:149], v[188:191], v[134:137]
	v_mfma_i32_16x16x64_i8 v[118:121], v[146:149], v[196:199], v[118:121]
	v_mfma_i32_16x16x64_i8 v[102:105], v[146:149], v[204:207], v[102:105]
	v_mfma_i32_16x16x64_i8 v[86:89], v[146:149], v[212:215], v[86:89]
	v_mfma_i32_16x16x64_i8 v[130:133], v[174:177], v[188:191], v[130:133]
	v_mfma_i32_16x16x64_i8 v[114:117], v[174:177], v[196:199], v[114:117]
	v_mfma_i32_16x16x64_i8 v[98:101], v[174:177], v[204:207], v[98:101]
	v_mfma_i32_16x16x64_i8 v[82:85], v[174:177], v[212:215], v[82:85]
	v_mfma_i32_16x16x64_i8 v[134:137], v[150:153], v[192:195], v[134:137]
	v_mfma_i32_16x16x64_i8 v[118:121], v[150:153], v[200:203], v[118:121]
	v_mfma_i32_16x16x64_i8 v[102:105], v[150:153], v[208:211], v[102:105]
	v_mfma_i32_16x16x64_i8 v[86:89], v[150:153], v[216:219], v[86:89]
	v_mfma_i32_16x16x64_i8 v[130:133], v[184:187], v[192:195], v[130:133]
	v_mfma_i32_16x16x64_i8 v[114:117], v[184:187], v[200:203], v[114:117]
	v_mfma_i32_16x16x64_i8 v[98:101], v[184:187], v[208:211], v[98:101]
	v_mfma_i32_16x16x64_i8 v[82:85], v[184:187], v[216:219], v[82:85]
	s_setprio 0
	s_barrier
	s_add_i32 s50, s41, s30
	s_mov_b32 m0, s50
	ds_read_b128 v[188:191], v182 offset:16384
	ds_read_b128 v[192:195], v182 offset:17408
	ds_read_b128 v[196:199], v182 offset:18432
	ds_read_b128 v[200:203], v182 offset:19456
	ds_read_b128 v[204:207], v182 offset:20480
	ds_read_b128 v[208:211], v182 offset:21504
	ds_read_b128 v[212:215], v182 offset:22528
	ds_read_b128 v[216:219], v182 offset:23552
	global_load_lds_dwordx4 v158, s[22:23]
	s_add_i32 m0, s50, 0x2000
	s_add_u32 s50, s22, 0x4000
	s_addc_u32 s51, s23, 0
	s_add_i32 s52, s42, s30
	global_load_lds_dwordx4 v162, s[22:23]
	s_mov_b32 m0, s52
	s_nop 0
	global_load_lds_dwordx4 v158, s[50:51]
	s_add_i32 m0, s52, 0x2000
	s_nop 0
	global_load_lds_dwordx4 v162, s[50:51]
	s_waitcnt vmcnt(6)
	s_waitcnt lgkmcnt(0)
	s_barrier
	s_setprio 1
	s_waitcnt lgkmcnt(0)
	v_mfma_i32_16x16x64_i8 v[62:65], v[66:69], v[188:191], v[62:65]
	v_mfma_i32_16x16x64_i8 v[46:49], v[66:69], v[196:199], v[46:49]
	v_mfma_i32_16x16x64_i8 v[30:33], v[66:69], v[204:207], v[30:33]
	v_mfma_i32_16x16x64_i8 v[14:17], v[66:69], v[212:215], v[14:17]
	v_mfma_i32_16x16x64_i8 v[58:61], v[74:77], v[188:191], v[58:61]
	v_mfma_i32_16x16x64_i8 v[42:45], v[74:77], v[196:199], v[42:45]
	v_mfma_i32_16x16x64_i8 v[26:29], v[74:77], v[204:207], v[26:29]
	v_mfma_i32_16x16x64_i8 v[10:13], v[74:77], v[212:215], v[10:13]
	v_mfma_i32_16x16x64_i8 v[62:65], v[70:73], v[192:195], v[62:65]
	v_mfma_i32_16x16x64_i8 v[46:49], v[70:73], v[200:203], v[46:49]
	v_mfma_i32_16x16x64_i8 v[30:33], v[70:73], v[208:211], v[30:33]
	v_mfma_i32_16x16x64_i8 v[14:17], v[70:73], v[216:219], v[14:17]
	v_mfma_i32_16x16x64_i8 v[58:61], v[78:81], v[192:195], v[58:61]
	v_mfma_i32_16x16x64_i8 v[42:45], v[78:81], v[200:203], v[42:45]
	v_mfma_i32_16x16x64_i8 v[26:29], v[78:81], v[208:211], v[26:29]
	v_mfma_i32_16x16x64_i8 v[10:13], v[78:81], v[216:219], v[10:13]
	s_setprio 0
	s_setprio 1
	v_mfma_i32_16x16x64_i8 v[54:57], v[146:149], v[188:191], v[54:57]
	v_mfma_i32_16x16x64_i8 v[38:41], v[146:149], v[196:199], v[38:41]
	v_mfma_i32_16x16x64_i8 v[22:25], v[146:149], v[204:207], v[22:25]
	v_mfma_i32_16x16x64_i8 v[6:9], v[146:149], v[212:215], v[6:9]
	v_mfma_i32_16x16x64_i8 v[50:53], v[174:177], v[188:191], v[50:53]
	v_mfma_i32_16x16x64_i8 v[34:37], v[174:177], v[196:199], v[34:37]
	v_mfma_i32_16x16x64_i8 v[18:21], v[174:177], v[204:207], v[18:21]
	v_mfma_i32_16x16x64_i8 v[2:5], v[174:177], v[212:215], v[2:5]
	v_mfma_i32_16x16x64_i8 v[54:57], v[150:153], v[192:195], v[54:57]
	v_mfma_i32_16x16x64_i8 v[38:41], v[150:153], v[200:203], v[38:41]
	v_mfma_i32_16x16x64_i8 v[22:25], v[150:153], v[208:211], v[22:25]
	v_mfma_i32_16x16x64_i8 v[6:9], v[150:153], v[216:219], v[6:9]
	v_mfma_i32_16x16x64_i8 v[50:53], v[184:187], v[192:195], v[50:53]
	v_mfma_i32_16x16x64_i8 v[34:37], v[184:187], v[200:203], v[34:37]
	v_mfma_i32_16x16x64_i8 v[18:21], v[184:187], v[208:211], v[18:21]
	v_mfma_i32_16x16x64_i8 v[2:5], v[184:187], v[216:219], v[2:5]
	s_setprio 0
	s_barrier
; #define PG8_STAGE(bufoff, gbase, voff) do { _Pragma("unroll") for (int _i = 0; _i < 2; ++_i) \
;         __builtin_amdgcn_global_load_lds((const unsigned*)((const char*)(gbase) + (voff)[_i]), (LAS unsigned*)(lds + (bufoff) + ldsw + _i * 8192), 16, 0, 0); } while (0)
; #define PG8_LDA(dst, b, h) do { _Pragma("unroll") for (int m = 0; m < 4; ++m) _Pragma("unroll") for (int k = 0; k < 2; ++k) dst[m][k] = *(const LAS bf16x8*)(lds + PG8_SA(b, h) + aoff + m * 2048 + k * 1024); } while (0)
; #define PG8_LDB(dst, b, h) do { _Pragma("unroll") for (int n = 0; n < 2; ++n) _Pragma("unroll") for (int k = 0; k < 2; ++k) dst[n][k] = *(const LAS bf16x8*)(lds + PG8_SB(b, h) + boff + n * 2048 + k * 1024); } while (0)
; #define PG8_WAIT_V(n) asm volatile("s_waitcnt vmcnt(" #n ")" ::: "memory")
; template <class Epi, class Sched, bool I8 = false>
; __device__ __forceinline__ void gemm_phase(LAS unsigned char* lds, const Gemm g, const Sched& S, const Epi& E) {
;     ...
;         for (int t = 0; t < nt; t += 2) {
;             const bool last = (t == nt - 2);
;             const char* a1 = cA + (size_t)(t + 1) * kstep;
;             const char* a2 = last ? nA : cA + (size_t)(t + 2) * kstep; const char* b2 = last ? nB : cB + (size_t)(t + 2) * kstep;
;             const char* a3 = a2 + kstep; const char* b3 = b2 + kstep;
;             PG8_LDB(B0, 0, 0); PG8_LDB(B1, 0, 1); PG8_SCHED; PG8_LDA(At, 0, 0); PG8_STAGE(PG8_SA(1, 1), a1 + hstepA, voffA);
;             PG8_WAIT_V(8); PG8_WAIT_L(0); PG8_BAR; PG8_MMA(0, 0, At, B0); PG8_MMA(0, 1, At, B1); PG8_BAR; PG8_SCHED;
;             PG8_LDA(At, 0, 1); PG8_STAGE(PG8_SB(0, 0), b2, voffB); PG8_STAGE(PG8_SB(0, 1), b2 + hstepB, voffB); PG8_STAGE(PG8_SA(0, 0), a2, voffA);
;             PG8_WAIT_V(8); PG8_WAIT_L(0); PG8_BAR; PG8_MMA(1, 0, At, B0); PG8_MMA(1, 1, At, B1); PG8_BAR; PG8_SCHED;
;             PG8_LDB(B0, 1, 0); PG8_LDB(B1, 1, 1); PG8_SCHED; PG8_LDA(At, 1, 0); PG8_STAGE(PG8_SA(0, 1), a2 + hstepA, voffA);
;             PG8_WAIT_V(8); PG8_WAIT_L(0); PG8_BAR; PG8_MMA(0, 0, At, B0); PG8_MMA(0, 1, At, B1); PG8_BAR; PG8_SCHED;
;             PG8_LDA(At, 1, 1); PG8_STAGE(PG8_SB(1, 0), b3, voffB); PG8_STAGE(PG8_SB(1, 1), b3 + hstepB, voffB); PG8_STAGE(PG8_SA(1, 0), a3, voffA);
;             PG8_WAIT_V(8); PG8_WAIT_L(0); PG8_BAR; PG8_MMA(1, 0, At, B0); PG8_MMA(1, 1, At, B1); PG8_BAR; PG8_SCHED;
;         }
;         if (wr == 0) PG8_BAR;
	s_add_i32 s50, 0, 0x18000
	s_add_i32 s51, 0, 0x1c000
	v_add_u32_e32 v78, s50, v178
	v_add_u32_e32 v164, s51, v178
	ds_read_b128 v[66:69], v78
	ds_read_b128 v[70:73], v78 offset:1024
	ds_read_b128 v[74:77], v78 offset:2048
	ds_read_b128 v[78:81], v78 offset:3072
	ds_read_b128 v[146:149], v164
	ds_read_b128 v[150:153], v164 offset:1024
	ds_read_b128 v[174:177], v164 offset:2048
	ds_read_b128 v[184:187], v164 offset:3072
	s_mov_b32 m0, s31
	s_nop 0
	global_load_lds_dwordx4 v156, s[24:25]
	s_mov_b32 m0, s33
	s_nop 0
	global_load_lds_dwordx4 v160, s[24:25]
	s_add_u32 s24, s24, 0x4000
	s_addc_u32 s25, s25, 0
	s_mov_b32 m0, s34
	ds_read_b128 v[188:191], v182 offset:32768
	ds_read_b128 v[192:195], v182 offset:33792
	ds_read_b128 v[196:199], v182 offset:34816
	ds_read_b128 v[200:203], v182 offset:35840
	ds_read_b128 v[204:207], v182 offset:36864
	ds_read_b128 v[208:211], v182 offset:37888
	ds_read_b128 v[212:215], v182 offset:38912
	ds_read_b128 v[216:219], v182 offset:39936
	global_load_lds_dwordx4 v156, s[24:25]
	s_mov_b32 m0, s35
	s_nop 0
	global_load_lds_dwordx4 v160, s[24:25]
	s_waitcnt vmcnt(8)
	s_waitcnt lgkmcnt(0)
	s_barrier
	s_setprio 1
	s_waitcnt lgkmcnt(0)
	v_mfma_i32_16x16x64_i8 v[142:145], v[66:69], v[188:191], v[142:145]
	v_mfma_i32_16x16x64_i8 v[126:129], v[66:69], v[196:199], v[126:129]
	v_mfma_i32_16x16x64_i8 v[110:113], v[66:69], v[204:207], v[110:113]
	v_mfma_i32_16x16x64_i8 v[94:97], v[66:69], v[212:215], v[94:97]
	v_mfma_i32_16x16x64_i8 v[138:141], v[74:77], v[188:191], v[138:141]
	v_mfma_i32_16x16x64_i8 v[122:125], v[74:77], v[196:199], v[122:125]
	v_mfma_i32_16x16x64_i8 v[106:109], v[74:77], v[204:207], v[106:109]
	v_mfma_i32_16x16x64_i8 v[90:93], v[74:77], v[212:215], v[90:93]
	v_mfma_i32_16x16x64_i8 v[142:145], v[70:73], v[192:195], v[142:145]
	v_mfma_i32_16x16x64_i8 v[126:129], v[70:73], v[200:203], v[126:129]
	v_mfma_i32_16x16x64_i8 v[110:113], v[70:73], v[208:211], v[110:113]
	v_mfma_i32_16x16x64_i8 v[94:97], v[70:73], v[216:219], v[94:97]
	v_mfma_i32_16x16x64_i8 v[138:141], v[78:81], v[192:195], v[138:141]
	v_mfma_i32_16x16x64_i8 v[122:125], v[78:81], v[200:203], v[122:125]
	v_mfma_i32_16x16x64_i8 v[106:109], v[78:81], v[208:211], v[106:109]
	v_mfma_i32_16x16x64_i8 v[90:93], v[78:81], v[216:219], v[90:93]
	s_setprio 0
	s_setprio 1
	v_mfma_i32_16x16x64_i8 v[134:137], v[146:149], v[188:191], v[134:137]
	v_mfma_i32_16x16x64_i8 v[118:121], v[146:149], v[196:199], v[118:121]
	v_mfma_i32_16x16x64_i8 v[102:105], v[146:149], v[204:207], v[102:105]
	v_mfma_i32_16x16x64_i8 v[86:89], v[146:149], v[212:215], v[86:89]
	v_mfma_i32_16x16x64_i8 v[130:133], v[174:177], v[188:191], v[130:133]
	v_mfma_i32_16x16x64_i8 v[114:117], v[174:177], v[196:199], v[114:117]
	v_mfma_i32_16x16x64_i8 v[98:101], v[174:177], v[204:207], v[98:101]
	v_mfma_i32_16x16x64_i8 v[82:85], v[174:177], v[212:215], v[82:85]
	v_mfma_i32_16x16x64_i8 v[134:137], v[150:153], v[192:195], v[134:137]
	v_mfma_i32_16x16x64_i8 v[118:121], v[150:153], v[200:203], v[118:121]
	v_mfma_i32_16x16x64_i8 v[102:105], v[150:153], v[208:211], v[102:105]
	v_mfma_i32_16x16x64_i8 v[86:89], v[150:153], v[216:219], v[86:89]
	v_mfma_i32_16x16x64_i8 v[130:133], v[184:187], v[192:195], v[130:133]
	v_mfma_i32_16x16x64_i8 v[114:117], v[184:187], v[200:203], v[114:117]
	v_mfma_i32_16x16x64_i8 v[98:101], v[184:187], v[208:211], v[98:101]
	v_mfma_i32_16x16x64_i8 v[82:85], v[184:187], v[216:219], v[82:85]
	s_setprio 0
	s_barrier
	s_add_u32 s24, s22, 0x8000
	s_addc_u32 s25, s23, 0
	s_add_i32 s50, s50, s30
	s_mov_b32 m0, s50
	ds_read_b128 v[188:191], v182 offset:49152
	ds_read_b128 v[192:195], v182 offset:50176
	ds_read_b128 v[196:199], v182 offset:51200
	ds_read_b128 v[200:203], v182 offset:52224
	ds_read_b128 v[204:207], v182 offset:53248
	ds_read_b128 v[208:211], v182 offset:54272
	ds_read_b128 v[212:215], v182 offset:55296
	ds_read_b128 v[216:219], v182 offset:56320
	global_load_lds_dwordx4 v158, s[24:25]
	s_add_i32 m0, s50, 0x2000
	s_add_u32 s22, s22, 0xc000
	v_lshl_add_u64 v[220:221], s[24:25], 0, v[162:163]
	s_addc_u32 s23, s23, 0
	s_add_i32 s24, s51, s30
	global_load_lds_dwordx4 v[220:221], off
	s_mov_b32 m0, s24
	s_nop 0
	global_load_lds_dwordx4 v158, s[22:23]
	s_add_i32 m0, s24, 0x2000
	s_nop 0
	global_load_lds_dwordx4 v162, s[22:23]
	s_waitcnt vmcnt(6)
	s_waitcnt lgkmcnt(0)
	s_barrier
	s_setprio 1
	s_waitcnt lgkmcnt(0)
	v_mfma_i32_16x16x64_i8 v[62:65], v[66:69], v[188:191], v[62:65]
	v_mfma_i32_16x16x64_i8 v[46:49], v[66:69], v[196:199], v[46:49]
	v_mfma_i32_16x16x64_i8 v[30:33], v[66:69], v[204:207], v[30:33]
	v_mfma_i32_16x16x64_i8 v[14:17], v[66:69], v[212:215], v[14:17]
	v_mfma_i32_16x16x64_i8 v[58:61], v[74:77], v[188:191], v[58:61]
	v_mfma_i32_16x16x64_i8 v[42:45], v[74:77], v[196:199], v[42:45]
	v_mfma_i32_16x16x64_i8 v[26:29], v[74:77], v[204:207], v[26:29]
	v_mfma_i32_16x16x64_i8 v[10:13], v[74:77], v[212:215], v[10:13]
	v_mfma_i32_16x16x64_i8 v[62:65], v[70:73], v[192:195], v[62:65]
	v_mfma_i32_16x16x64_i8 v[46:49], v[70:73], v[200:203], v[46:49]
	v_mfma_i32_16x16x64_i8 v[30:33], v[70:73], v[208:211], v[30:33]
	v_mfma_i32_16x16x64_i8 v[14:17], v[70:73], v[216:219], v[14:17]
	v_mfma_i32_16x16x64_i8 v[58:61], v[78:81], v[192:195], v[58:61]
	v_mfma_i32_16x16x64_i8 v[42:45], v[78:81], v[200:203], v[42:45]
	v_mfma_i32_16x16x64_i8 v[26:29], v[78:81], v[208:211], v[26:29]
	v_mfma_i32_16x16x64_i8 v[10:13], v[78:81], v[216:219], v[10:13]
	s_setprio 0
	s_setprio 1
	v_mfma_i32_16x16x64_i8 v[54:57], v[146:149], v[188:191], v[54:57]
	v_mfma_i32_16x16x64_i8 v[38:41], v[146:149], v[196:199], v[38:41]
	v_mfma_i32_16x16x64_i8 v[22:25], v[146:149], v[204:207], v[22:25]
	v_mfma_i32_16x16x64_i8 v[6:9], v[146:149], v[212:215], v[6:9]
	v_mfma_i32_16x16x64_i8 v[50:53], v[174:177], v[188:191], v[50:53]
	v_mfma_i32_16x16x64_i8 v[34:37], v[174:177], v[196:199], v[34:37]
	v_mfma_i32_16x16x64_i8 v[18:21], v[174:177], v[204:207], v[18:21]
	v_mfma_i32_16x16x64_i8 v[2:5], v[174:177], v[212:215], v[2:5]
	v_mfma_i32_16x16x64_i8 v[54:57], v[150:153], v[192:195], v[54:57]
	v_mfma_i32_16x16x64_i8 v[38:41], v[150:153], v[200:203], v[38:41]
	v_mfma_i32_16x16x64_i8 v[22:25], v[150:153], v[208:211], v[22:25]
	v_mfma_i32_16x16x64_i8 v[6:9], v[150:153], v[216:219], v[6:9]
	v_mfma_i32_16x16x64_i8 v[50:53], v[184:187], v[192:195], v[50:53]
	v_mfma_i32_16x16x64_i8 v[34:37], v[184:187], v[200:203], v[34:37]
	v_mfma_i32_16x16x64_i8 v[18:21], v[184:187], v[208:211], v[18:21]
	v_mfma_i32_16x16x64_i8 v[2:5], v[184:187], v[216:219], v[2:5]
	s_setprio 0
	s_barrier
	s_add_i32 s49, s49, 2
	s_add_u32 s18, s18, 0x10000
	s_addc_u32 s19, s19, 0
	s_add_u32 s47, s47, 0x10000
	s_addc_u32 s48, s48, 0
	s_cmpk_gt_u32 s49, 0x53
	s_cbranch_scc0 .LBB0_1393
	s_and_b64 vcc, exec, s[14:15]
	s_cbranch_vccz .LBB0_1396
	s_barrier

; #define PG8_STAGE(bufoff, gbase, voff) do { _Pragma("unroll") for (int _i = 0; _i < 2; ++_i) \
;         __builtin_amdgcn_global_load_lds((const unsigned*)((const char*)(gbase) + (voff)[_i]), (LAS unsigned*)(lds + (bufoff) + ldsw + _i * 8192), 16, 0, 0); } while (0)
; #define PG8_LDA(dst, b, h) do { _Pragma("unroll") for (int m = 0; m < 4; ++m) _Pragma("unroll") for (int k = 0; k < 2; ++k) dst[m][k] = *(const LAS bf16x8*)(lds + PG8_SA(b, h) + aoff + m * 2048 + k * 1024); } while (0)
; #define PG8_LDB(dst, b, h) do { _Pragma("unroll") for (int n = 0; n < 2; ++n) _Pragma("unroll") for (int k = 0; k < 2; ++k) dst[n][k] = *(const LAS bf16x8*)(lds + PG8_SB(b, h) + boff + n * 2048 + k * 1024); } while (0)
; #define PG8_WAIT_V(n) asm volatile("s_waitcnt vmcnt(" #n ")" ::: "memory")
; #define PG8_WAIT_L(n) asm volatile("s_waitcnt lgkmcnt(" #n ")" ::: "memory")
; #define PG8_BAR __builtin_amdgcn_s_barrier()
; #define PG8_SCHED __builtin_amdgcn_sched_barrier(0)
; template <class Epi, class Sched, bool I8 = false>
; __device__ __forceinline__ void gemm_phase(LAS unsigned char* lds, const Gemm g, const Sched& S, const Epi& E) {
;     ...
;         for (int t = 0; t < nt; t += 2) {
;             const bool last = (t == nt - 2);
;             const char* a1 = cA + (size_t)(t + 1) * kstep;
;             const char* a2 = last ? nA : cA + (size_t)(t + 2) * kstep; const char* b2 = last ? nB : cB + (size_t)(t + 2) * kstep;
;             const char* a3 = a2 + kstep; const char* b3 = b2 + kstep;
;             PG8_LDB(B0, 0, 0); PG8_LDB(B1, 0, 1); PG8_SCHED; PG8_LDA(At, 0, 0); PG8_STAGE(PG8_SA(1, 1), a1 + hstepA, voffA);
;             PG8_WAIT_V(8); PG8_WAIT_L(0); PG8_BAR; PG8_MMA(0, 0, At, B0); PG8_MMA(0, 1, At, B1); PG8_BAR; PG8_SCHED;
;             PG8_LDA(At, 0, 1); PG8_STAGE(PG8_SB(0, 0), b2, voffB); PG8_STAGE(PG8_SB(0, 1), b2 + hstepB, voffB); PG8_STAGE(PG8_SA(0, 0), a2, voffA);
;             PG8_WAIT_V(8); PG8_WAIT_L(0); PG8_BAR; PG8_MMA(1, 0, At, B0); PG8_MMA(1, 1, At, B1); PG8_BAR; PG8_SCHED;
.LBB0_1482:
	ds_read_b128 v[152:155], v182
	ds_read_b128 v[156:159], v182 offset:1024
	ds_read_b128 v[160:163], v182 offset:2048
	ds_read_b128 v[164:167], v182 offset:3072
	ds_read_b128 v[168:171], v183
	ds_read_b128 v[172:175], v183 offset:1024
	ds_read_b128 v[176:179], v183 offset:2048
	ds_read_b128 v[186:189], v183 offset:3072
	s_add_u32 s38, s8, 0x4000
	s_addc_u32 s39, s9, 0
	s_cmp_eq_u32 s47, 60
	s_cselect_b32 s42, s31, s38
	s_cselect_b32 s43, s7, s39
	s_cselect_b32 s40, s44, s45
	s_cselect_b32 s41, s29, s46
	s_add_u32 s38, s42, 0x8000
	s_addc_u32 s39, s43, 0
	s_sub_u32 s98, s8, 0x4000
	s_subb_u32 s99, s9, 0
	s_mov_b32 m0, s58
	s_nop 0
	global_load_lds_dwordx4 v130, s[98:99]
	s_mov_b32 m0, s59
	s_nop 0
	global_load_lds_dwordx4 v134, s[98:99]
	s_add_i32 m0, s33, 0xc000
	ds_read_b128 v[190:193], v184
	ds_read_b128 v[194:197], v184 offset:1024
	ds_read_b128 v[198:201], v184 offset:2048
	ds_read_b128 v[202:205], v184 offset:3072
	ds_read_b128 v[206:209], v184 offset:4096
	ds_read_b128 v[210:213], v184 offset:5120
	ds_read_b128 v[214:217], v184 offset:6144
	ds_read_b128 v[218:221], v184 offset:7168
	global_load_lds_dwordx4 v144, s[8:9]
	s_add_i32 m0, s33, 0xe000
	s_nop 0
	global_load_lds_dwordx4 v146, s[8:9]
	s_waitcnt vmcnt(8)
	s_waitcnt lgkmcnt(0)
	s_barrier
	s_setprio 1
	s_waitcnt lgkmcnt(0)
	v_mfma_f32_16x16x32_bf16 v[126:129], v[152:155], v[190:193], v[126:129]
	v_mfma_f32_16x16x32_bf16 v[110:113], v[152:155], v[198:201], v[110:113]
	v_mfma_f32_16x16x32_bf16 v[94:97], v[152:155], v[206:209], v[94:97]
	v_mfma_f32_16x16x32_bf16 v[78:81], v[152:155], v[214:217], v[78:81]
	v_mfma_f32_16x16x32_bf16 v[122:125], v[160:163], v[190:193], v[122:125]
	v_mfma_f32_16x16x32_bf16 v[106:109], v[160:163], v[198:201], v[106:109]
	v_mfma_f32_16x16x32_bf16 v[90:93], v[160:163], v[206:209], v[90:93]
	v_mfma_f32_16x16x32_bf16 v[74:77], v[160:163], v[214:217], v[74:77]
	v_mfma_f32_16x16x32_bf16 v[126:129], v[156:159], v[194:197], v[126:129]
	v_mfma_f32_16x16x32_bf16 v[110:113], v[156:159], v[202:205], v[110:113]
	v_mfma_f32_16x16x32_bf16 v[94:97], v[156:159], v[210:213], v[94:97]
	v_mfma_f32_16x16x32_bf16 v[78:81], v[156:159], v[218:221], v[78:81]
	v_mfma_f32_16x16x32_bf16 v[122:125], v[164:167], v[194:197], v[122:125]
	v_mfma_f32_16x16x32_bf16 v[106:109], v[164:167], v[202:205], v[106:109]
	v_mfma_f32_16x16x32_bf16 v[90:93], v[164:167], v[210:213], v[90:93]
	v_mfma_f32_16x16x32_bf16 v[74:77], v[164:167], v[218:221], v[74:77]
	s_setprio 0
	s_setprio 1
	v_mfma_f32_16x16x32_bf16 v[118:121], v[168:171], v[190:193], v[118:121]
	v_mfma_f32_16x16x32_bf16 v[102:105], v[168:171], v[198:201], v[102:105]
	v_mfma_f32_16x16x32_bf16 v[86:89], v[168:171], v[206:209], v[86:89]
	v_mfma_f32_16x16x32_bf16 v[70:73], v[168:171], v[214:217], v[70:73]
	v_mfma_f32_16x16x32_bf16 v[114:117], v[176:179], v[190:193], v[114:117]
	v_mfma_f32_16x16x32_bf16 v[98:101], v[176:179], v[198:201], v[98:101]
	v_mfma_f32_16x16x32_bf16 v[82:85], v[176:179], v[206:209], v[82:85]
	v_mfma_f32_16x16x32_bf16 v[66:69], v[176:179], v[214:217], v[66:69]
	v_mfma_f32_16x16x32_bf16 v[118:121], v[172:175], v[194:197], v[118:121]
	v_mfma_f32_16x16x32_bf16 v[102:105], v[172:175], v[202:205], v[102:105]
	v_mfma_f32_16x16x32_bf16 v[86:89], v[172:175], v[210:213], v[86:89]
	v_mfma_f32_16x16x32_bf16 v[70:73], v[172:175], v[218:221], v[70:73]
	v_mfma_f32_16x16x32_bf16 v[114:117], v[186:189], v[194:197], v[114:117]
	v_mfma_f32_16x16x32_bf16 v[98:101], v[186:189], v[202:205], v[98:101]
	v_mfma_f32_16x16x32_bf16 v[82:85], v[186:189], v[210:213], v[82:85]
	v_mfma_f32_16x16x32_bf16 v[66:69], v[186:189], v[218:221], v[66:69]
	s_setprio 0
	s_barrier
	s_add_i32 s48, s63, s25
	s_mov_b32 m0, s48
	ds_read_b128 v[190:193], v184 offset:16384
	ds_read_b128 v[194:197], v184 offset:17408
	ds_read_b128 v[198:201], v184 offset:18432
	ds_read_b128 v[202:205], v184 offset:19456
	ds_read_b128 v[206:209], v184 offset:20480
	ds_read_b128 v[210:213], v184 offset:21504
	ds_read_b128 v[214:217], v184 offset:22528
	ds_read_b128 v[218:221], v184 offset:23552
	global_load_lds_dwordx4 v132, s[40:41]
	s_add_i32 m0, s48, 0x2000
	s_add_u32 s48, s40, 0x4000
	s_addc_u32 s49, s41, 0
	s_add_i32 s50, s64, s25
	global_load_lds_dwordx4 v136, s[40:41]
	s_mov_b32 m0, s50
	s_nop 0
	global_load_lds_dwordx4 v132, s[48:49]
	s_add_i32 m0, s50, 0x2000
	s_nop 0
	global_load_lds_dwordx4 v136, s[48:49]
	s_waitcnt vmcnt(6)
	s_waitcnt lgkmcnt(0)
	s_barrier
	s_setprio 1
	s_waitcnt lgkmcnt(0)
	v_mfma_f32_16x16x32_bf16 v[62:65], v[152:155], v[190:193], v[62:65]
	v_mfma_f32_16x16x32_bf16 v[46:49], v[152:155], v[198:201], v[46:49]
	v_mfma_f32_16x16x32_bf16 v[30:33], v[152:155], v[206:209], v[30:33]
	v_mfma_f32_16x16x32_bf16 v[14:17], v[152:155], v[214:217], v[14:17]
	v_mfma_f32_16x16x32_bf16 v[58:61], v[160:163], v[190:193], v[58:61]
	v_mfma_f32_16x16x32_bf16 v[42:45], v[160:163], v[198:201], v[42:45]
	v_mfma_f32_16x16x32_bf16 v[26:29], v[160:163], v[206:209], v[26:29]
	v_mfma_f32_16x16x32_bf16 v[10:13], v[160:163], v[214:217], v[10:13]
	v_mfma_f32_16x16x32_bf16 v[62:65], v[156:159], v[194:197], v[62:65]
	v_mfma_f32_16x16x32_bf16 v[46:49], v[156:159], v[202:205], v[46:49]
	v_mfma_f32_16x16x32_bf16 v[30:33], v[156:159], v[210:213], v[30:33]
	v_mfma_f32_16x16x32_bf16 v[14:17], v[156:159], v[218:221], v[14:17]
	v_mfma_f32_16x16x32_bf16 v[58:61], v[164:167], v[194:197], v[58:61]
	v_mfma_f32_16x16x32_bf16 v[42:45], v[164:167], v[202:205], v[42:45]
	v_mfma_f32_16x16x32_bf16 v[26:29], v[164:167], v[210:213], v[26:29]
	v_mfma_f32_16x16x32_bf16 v[10:13], v[164:167], v[218:221], v[10:13]
	s_setprio 0
	s_setprio 1
	v_mfma_f32_16x16x32_bf16 v[54:57], v[168:171], v[190:193], v[54:57]
	v_mfma_f32_16x16x32_bf16 v[38:41], v[168:171], v[198:201], v[38:41]
	v_mfma_f32_16x16x32_bf16 v[22:25], v[168:171], v[206:209], v[22:25]
	v_mfma_f32_16x16x32_bf16 v[6:9], v[168:171], v[214:217], v[6:9]
	v_mfma_f32_16x16x32_bf16 v[50:53], v[176:179], v[190:193], v[50:53]
	v_mfma_f32_16x16x32_bf16 v[34:37], v[176:179], v[198:201], v[34:37]
	v_mfma_f32_16x16x32_bf16 v[18:21], v[176:179], v[206:209], v[18:21]
	v_mfma_f32_16x16x32_bf16 v[2:5], v[176:179], v[214:217], v[2:5]
	v_mfma_f32_16x16x32_bf16 v[54:57], v[172:175], v[194:197], v[54:57]
	v_mfma_f32_16x16x32_bf16 v[38:41], v[172:175], v[202:205], v[38:41]
	v_mfma_f32_16x16x32_bf16 v[22:25], v[172:175], v[210:213], v[22:25]
	v_mfma_f32_16x16x32_bf16 v[6:9], v[172:175], v[218:221], v[6:9]
	v_mfma_f32_16x16x32_bf16 v[50:53], v[186:189], v[194:197], v[50:53]
	v_mfma_f32_16x16x32_bf16 v[34:37], v[186:189], v[202:205], v[34:37]
	v_mfma_f32_16x16x32_bf16 v[18:21], v[186:189], v[210:213], v[18:21]
	v_mfma_f32_16x16x32_bf16 v[2:5], v[186:189], v[218:221], v[2:5]
	s_setprio 0
	s_barrier
; #define PG8_STAGE(bufoff, gbase, voff) do { _Pragma("unroll") for (int _i = 0; _i < 2; ++_i) \
;         __builtin_amdgcn_global_load_lds((const unsigned*)((const char*)(gbase) + (voff)[_i]), (LAS unsigned*)(lds + (bufoff) + ldsw + _i * 8192), 16, 0, 0); } while (0)
; #define PG8_LDA(dst, b, h) do { _Pragma("unroll") for (int m = 0; m < 4; ++m) _Pragma("unroll") for (int k = 0; k < 2; ++k) dst[m][k] = *(const LAS bf16x8*)(lds + PG8_SA(b, h) + aoff + m * 2048 + k * 1024); } while (0)
; #define PG8_LDB(dst, b, h) do { _Pragma("unroll") for (int n = 0; n < 2; ++n) _Pragma("unroll") for (int k = 0; k < 2; ++k) dst[n][k] = *(const LAS bf16x8*)(lds + PG8_SB(b, h) + boff + n * 2048 + k * 1024); } while (0)
; #define PG8_WAIT_V(n) asm volatile("s_waitcnt vmcnt(" #n ")" ::: "memory")
; #define PG8_WAIT_L(n) asm volatile("s_waitcnt lgkmcnt(" #n ")" ::: "memory")
; #define PG8_BAR __builtin_amdgcn_s_barrier()
; #define PG8_SCHED __builtin_amdgcn_sched_barrier(0)
; template <class Epi, class Sched, bool I8 = false>
; __device__ __forceinline__ void gemm_phase(LAS unsigned char* lds, const Gemm g, const Sched& S, const Epi& E) {
;     ...
;             PG8_LDB(B0, 1, 0); PG8_LDB(B1, 1, 1); PG8_SCHED; PG8_LDA(At, 1, 0); PG8_STAGE(PG8_SA(0, 1), a2 + hstepA, voffA);
;             PG8_WAIT_V(8); PG8_WAIT_L(0); PG8_BAR; PG8_MMA(0, 0, At, B0); PG8_MMA(0, 1, At, B1); PG8_BAR; PG8_SCHED;
;             PG8_LDA(At, 1, 1); PG8_STAGE(PG8_SB(1, 0), b3, voffB); PG8_STAGE(PG8_SB(1, 1), b3 + hstepB, voffB); PG8_STAGE(PG8_SA(1, 0), a3, voffA);
;             PG8_WAIT_V(8); PG8_WAIT_L(0); PG8_BAR; PG8_MMA(1, 0, At, B0); PG8_MMA(1, 1, At, B1); PG8_BAR; PG8_SCHED;
;         }
;         if (wr == 0) PG8_BAR;
	s_add_i32 s48, 0, 0x18000
	v_add_u32_e32 v138, s48, v181
	s_add_i32 s49, 0, 0x1c000
	ds_read_b128 v[152:155], v138
	ds_read_b128 v[156:159], v138 offset:1024
	ds_read_b128 v[160:163], v138 offset:2048
	ds_read_b128 v[164:167], v138 offset:3072
	v_add_u32_e32 v138, s49, v181
	ds_read_b128 v[168:171], v138
	ds_read_b128 v[172:175], v138 offset:1024
	ds_read_b128 v[176:179], v138 offset:2048
	ds_read_b128 v[186:189], v138 offset:3072
	s_mov_b32 m0, s33
	s_nop 0
	global_load_lds_dwordx4 v130, s[42:43]
	s_mov_b32 m0, s52
	s_nop 0
	global_load_lds_dwordx4 v134, s[42:43]
	s_add_u32 s42, s42, 0x4000
	s_addc_u32 s43, s43, 0
	s_mov_b32 m0, s53
	ds_read_b128 v[190:193], v184 offset:32768
	ds_read_b128 v[194:197], v184 offset:33792
	ds_read_b128 v[198:201], v184 offset:34816
	ds_read_b128 v[202:205], v184 offset:35840
	ds_read_b128 v[206:209], v184 offset:36864
	ds_read_b128 v[210:213], v184 offset:37888
	ds_read_b128 v[214:217], v184 offset:38912
	ds_read_b128 v[218:221], v184 offset:39936
	global_load_lds_dwordx4 v130, s[42:43]
	s_mov_b32 m0, s54
	s_nop 0
	global_load_lds_dwordx4 v134, s[42:43]
	s_waitcnt vmcnt(8)
	s_waitcnt lgkmcnt(0)
	s_barrier
	s_setprio 1
	s_waitcnt lgkmcnt(0)
	v_mfma_f32_16x16x32_bf16 v[126:129], v[152:155], v[190:193], v[126:129]
	v_mfma_f32_16x16x32_bf16 v[110:113], v[152:155], v[198:201], v[110:113]
	v_mfma_f32_16x16x32_bf16 v[94:97], v[152:155], v[206:209], v[94:97]
	v_mfma_f32_16x16x32_bf16 v[78:81], v[152:155], v[214:217], v[78:81]
	v_mfma_f32_16x16x32_bf16 v[122:125], v[160:163], v[190:193], v[122:125]
	v_mfma_f32_16x16x32_bf16 v[106:109], v[160:163], v[198:201], v[106:109]
	v_mfma_f32_16x16x32_bf16 v[90:93], v[160:163], v[206:209], v[90:93]
	v_mfma_f32_16x16x32_bf16 v[74:77], v[160:163], v[214:217], v[74:77]
	v_mfma_f32_16x16x32_bf16 v[126:129], v[156:159], v[194:197], v[126:129]
	v_mfma_f32_16x16x32_bf16 v[110:113], v[156:159], v[202:205], v[110:113]
	v_mfma_f32_16x16x32_bf16 v[94:97], v[156:159], v[210:213], v[94:97]
	v_mfma_f32_16x16x32_bf16 v[78:81], v[156:159], v[218:221], v[78:81]
	v_mfma_f32_16x16x32_bf16 v[122:125], v[164:167], v[194:197], v[122:125]
	v_mfma_f32_16x16x32_bf16 v[106:109], v[164:167], v[202:205], v[106:109]
	v_mfma_f32_16x16x32_bf16 v[90:93], v[164:167], v[210:213], v[90:93]
	v_mfma_f32_16x16x32_bf16 v[74:77], v[164:167], v[218:221], v[74:77]
	s_setprio 0
	s_setprio 1
	v_mfma_f32_16x16x32_bf16 v[118:121], v[168:171], v[190:193], v[118:121]
	v_mfma_f32_16x16x32_bf16 v[102:105], v[168:171], v[198:201], v[102:105]
	v_mfma_f32_16x16x32_bf16 v[86:89], v[168:171], v[206:209], v[86:89]
	v_mfma_f32_16x16x32_bf16 v[70:73], v[168:171], v[214:217], v[70:73]
	v_mfma_f32_16x16x32_bf16 v[114:117], v[176:179], v[190:193], v[114:117]
	v_mfma_f32_16x16x32_bf16 v[98:101], v[176:179], v[198:201], v[98:101]
	v_mfma_f32_16x16x32_bf16 v[82:85], v[176:179], v[206:209], v[82:85]
	v_mfma_f32_16x16x32_bf16 v[66:69], v[176:179], v[214:217], v[66:69]
	v_mfma_f32_16x16x32_bf16 v[118:121], v[172:175], v[194:197], v[118:121]
	v_mfma_f32_16x16x32_bf16 v[102:105], v[172:175], v[202:205], v[102:105]
	v_mfma_f32_16x16x32_bf16 v[86:89], v[172:175], v[210:213], v[86:89]
	v_mfma_f32_16x16x32_bf16 v[70:73], v[172:175], v[218:221], v[70:73]
	v_mfma_f32_16x16x32_bf16 v[114:117], v[186:189], v[194:197], v[114:117]
	v_mfma_f32_16x16x32_bf16 v[98:101], v[186:189], v[202:205], v[98:101]
	v_mfma_f32_16x16x32_bf16 v[82:85], v[186:189], v[210:213], v[82:85]
	v_mfma_f32_16x16x32_bf16 v[66:69], v[186:189], v[218:221], v[66:69]
	s_setprio 0
	s_barrier
	s_add_u32 s42, s40, 0x8000
	s_addc_u32 s43, s41, 0
	s_add_i32 s48, s48, s25
	s_mov_b32 m0, s48
	ds_read_b128 v[190:193], v184 offset:49152
	ds_read_b128 v[194:197], v184 offset:50176
	ds_read_b128 v[198:201], v184 offset:51200
	ds_read_b128 v[202:205], v184 offset:52224
	ds_read_b128 v[206:209], v184 offset:53248
	ds_read_b128 v[210:213], v184 offset:54272
	ds_read_b128 v[214:217], v184 offset:55296
	ds_read_b128 v[218:221], v184 offset:56320
	global_load_lds_dwordx4 v132, s[42:43]
	s_add_i32 m0, s48, 0x2000
	s_add_u32 s40, s40, 0xc000
	v_lshl_add_u64 v[222:223], s[42:43], 0, v[136:137]
	s_addc_u32 s41, s41, 0
	s_add_i32 s42, s49, s25
	global_load_lds_dwordx4 v[222:223], off
	s_mov_b32 m0, s42
	s_nop 0
	global_load_lds_dwordx4 v132, s[40:41]
	s_add_i32 m0, s42, 0x2000
	s_nop 0
	global_load_lds_dwordx4 v136, s[40:41]
	s_waitcnt vmcnt(6)
	s_waitcnt lgkmcnt(0)
	s_barrier
	s_setprio 1
	s_waitcnt lgkmcnt(0)
	v_mfma_f32_16x16x32_bf16 v[62:65], v[152:155], v[190:193], v[62:65]
	v_mfma_f32_16x16x32_bf16 v[46:49], v[152:155], v[198:201], v[46:49]
	v_mfma_f32_16x16x32_bf16 v[30:33], v[152:155], v[206:209], v[30:33]
	v_mfma_f32_16x16x32_bf16 v[14:17], v[152:155], v[214:217], v[14:17]
	v_mfma_f32_16x16x32_bf16 v[58:61], v[160:163], v[190:193], v[58:61]
	v_mfma_f32_16x16x32_bf16 v[42:45], v[160:163], v[198:201], v[42:45]
	v_mfma_f32_16x16x32_bf16 v[26:29], v[160:163], v[206:209], v[26:29]
	v_mfma_f32_16x16x32_bf16 v[10:13], v[160:163], v[214:217], v[10:13]
	v_mfma_f32_16x16x32_bf16 v[62:65], v[156:159], v[194:197], v[62:65]
	v_mfma_f32_16x16x32_bf16 v[46:49], v[156:159], v[202:205], v[46:49]
	v_mfma_f32_16x16x32_bf16 v[30:33], v[156:159], v[210:213], v[30:33]
	v_mfma_f32_16x16x32_bf16 v[14:17], v[156:159], v[218:221], v[14:17]
	v_mfma_f32_16x16x32_bf16 v[58:61], v[164:167], v[194:197], v[58:61]
	v_mfma_f32_16x16x32_bf16 v[42:45], v[164:167], v[202:205], v[42:45]
	v_mfma_f32_16x16x32_bf16 v[26:29], v[164:167], v[210:213], v[26:29]
	v_mfma_f32_16x16x32_bf16 v[10:13], v[164:167], v[218:221], v[10:13]
	s_setprio 0
	s_setprio 1
	v_mfma_f32_16x16x32_bf16 v[54:57], v[168:171], v[190:193], v[54:57]
	v_mfma_f32_16x16x32_bf16 v[38:41], v[168:171], v[198:201], v[38:41]
	v_mfma_f32_16x16x32_bf16 v[22:25], v[168:171], v[206:209], v[22:25]
	v_mfma_f32_16x16x32_bf16 v[6:9], v[168:171], v[214:217], v[6:9]
	v_mfma_f32_16x16x32_bf16 v[50:53], v[176:179], v[190:193], v[50:53]
	v_mfma_f32_16x16x32_bf16 v[34:37], v[176:179], v[198:201], v[34:37]
	v_mfma_f32_16x16x32_bf16 v[18:21], v[176:179], v[206:209], v[18:21]
	v_mfma_f32_16x16x32_bf16 v[2:5], v[176:179], v[214:217], v[2:5]
	v_mfma_f32_16x16x32_bf16 v[54:57], v[172:175], v[194:197], v[54:57]
	v_mfma_f32_16x16x32_bf16 v[38:41], v[172:175], v[202:205], v[38:41]
	v_mfma_f32_16x16x32_bf16 v[22:25], v[172:175], v[210:213], v[22:25]
	v_mfma_f32_16x16x32_bf16 v[6:9], v[172:175], v[218:221], v[6:9]
	v_mfma_f32_16x16x32_bf16 v[50:53], v[186:189], v[194:197], v[50:53]
	v_mfma_f32_16x16x32_bf16 v[34:37], v[186:189], v[202:205], v[34:37]
	v_mfma_f32_16x16x32_bf16 v[18:21], v[186:189], v[210:213], v[18:21]
	v_mfma_f32_16x16x32_bf16 v[2:5], v[186:189], v[218:221], v[2:5]
	s_setprio 0
	s_barrier
	s_add_i32 s47, s47, 2
	s_add_u32 s8, s8, 0x10000
	s_addc_u32 s9, s9, 0
	s_add_u32 s45, s45, 0x10000
	s_addc_u32 s46, s46, 0
	s_cmp_gt_u32 s47, 61
	s_cbranch_scc0 .LBB0_1482
	s_and_b64 vcc, exec, s[20:21]
	s_cbranch_vccz .LBB0_1485
	s_barrier

; #define PG8_STAGE(bufoff, gbase, voff) do { _Pragma("unroll") for (int _i = 0; _i < 2; ++_i) \
;         __builtin_amdgcn_global_load_lds((const unsigned*)((const char*)(gbase) + (voff)[_i]), (LAS unsigned*)(lds + (bufoff) + ldsw + _i * 8192), 16, 0, 0); } while (0)
; #define PG8_LDA(dst, b, h) do { _Pragma("unroll") for (int m = 0; m < 4; ++m) _Pragma("unroll") for (int k = 0; k < 2; ++k) dst[m][k] = *(const LAS bf16x8*)(lds + PG8_SA(b, h) + aoff + m * 2048 + k * 1024); } while (0)
; #define PG8_LDB(dst, b, h) do { _Pragma("unroll") for (int n = 0; n < 2; ++n) _Pragma("unroll") for (int k = 0; k < 2; ++k) dst[n][k] = *(const LAS bf16x8*)(lds + PG8_SB(b, h) + boff + n * 2048 + k * 1024); } while (0)
; #define PG8_WAIT_V(n) asm volatile("s_waitcnt vmcnt(" #n ")" ::: "memory")
; #define PG8_WAIT_L(n) asm volatile("s_waitcnt lgkmcnt(" #n ")" ::: "memory")
; #define PG8_BAR __builtin_amdgcn_s_barrier()
; #define PG8_SCHED __builtin_amdgcn_sched_barrier(0)
; template <class Epi, class Sched, bool I8 = false>
; __device__ __forceinline__ void gemm_phase(LAS unsigned char* lds, const Gemm g, const Sched& S, const Epi& E) {
;     ...
;         for (int t = 0; t < nt; t += 2) {
;             const bool last = (t == nt - 2);
;             const char* a1 = cA + (size_t)(t + 1) * kstep;
;             const char* a2 = last ? nA : cA + (size_t)(t + 2) * kstep; const char* b2 = last ? nB : cB + (size_t)(t + 2) * kstep;
;             const char* a3 = a2 + kstep; const char* b3 = b2 + kstep;
;             PG8_LDB(B0, 0, 0); PG8_LDB(B1, 0, 1); PG8_SCHED; PG8_LDA(At, 0, 0); PG8_STAGE(PG8_SA(1, 1), a1 + hstepA, voffA);
;             PG8_WAIT_V(8); PG8_WAIT_L(0); PG8_BAR; PG8_MMA(0, 0, At, B0); PG8_MMA(0, 1, At, B1); PG8_BAR; PG8_SCHED;
;             PG8_LDA(At, 0, 1); PG8_STAGE(PG8_SB(0, 0), b2, voffB); PG8_STAGE(PG8_SB(0, 1), b2 + hstepB, voffB); PG8_STAGE(PG8_SA(0, 0), a2, voffA);
;             PG8_WAIT_V(8); PG8_WAIT_L(0); PG8_BAR; PG8_MMA(1, 0, At, B0); PG8_MMA(1, 1, At, B1); PG8_BAR; PG8_SCHED;
.LBB0_2685:
	ds_read_b128 v[130:133], v166
	ds_read_b128 v[134:137], v166 offset:1024
	ds_read_b128 v[158:161], v166 offset:2048
	ds_read_b128 v[170:173], v166 offset:3072
	ds_read_b128 v[174:177], v167
	ds_read_b128 v[178:181], v167 offset:1024
	ds_read_b128 v[182:185], v167 offset:2048
	ds_read_b128 v[186:189], v167 offset:3072
	s_add_u32 s12, s10, 0x4000
	s_addc_u32 s13, s11, 0
	s_cmp_eq_u32 s45, 4
	s_cselect_b32 s16, s40, s12
	s_cselect_b32 s17, s39, s13
	s_cselect_b32 s14, s42, s43
	s_cselect_b32 s15, s41, s44
	s_add_u32 s12, s16, 0x8000
	s_addc_u32 s13, s17, 0
	s_sub_u32 s98, s10, 0x4000
	s_subb_u32 s99, s11, 0
	s_mov_b32 m0, s33
	s_nop 0
	global_load_lds_dwordx4 v144, s[98:99]
	s_mov_b32 m0, s34
	s_nop 0
	global_load_lds_dwordx4 v140, s[98:99]
	s_add_i32 m0, s26, 0xc000
	ds_read_b128 v[190:193], v168
	ds_read_b128 v[194:197], v168 offset:1024
	ds_read_b128 v[198:201], v168 offset:2048
	ds_read_b128 v[202:205], v168 offset:3072
	ds_read_b128 v[206:209], v168 offset:4096
	ds_read_b128 v[210:213], v168 offset:5120
	ds_read_b128 v[214:217], v168 offset:6144
	ds_read_b128 v[218:221], v168 offset:7168
	global_load_lds_dwordx4 v150, s[10:11]
	s_add_i32 m0, s26, 0xe000
	s_nop 0
	global_load_lds_dwordx4 v152, s[10:11]
	s_waitcnt vmcnt(8)
	s_waitcnt lgkmcnt(0)
	s_barrier
	s_setprio 1
	s_waitcnt lgkmcnt(0)
	v_mfma_f32_16x16x32_bf16 v[126:129], v[130:133], v[190:193], v[126:129]
	v_mfma_f32_16x16x32_bf16 v[118:121], v[130:133], v[198:201], v[118:121]
	v_mfma_f32_16x16x32_bf16 v[110:113], v[130:133], v[206:209], v[110:113]
	v_mfma_f32_16x16x32_bf16 v[102:105], v[130:133], v[214:217], v[102:105]
	v_mfma_f32_16x16x32_bf16 v[122:125], v[158:161], v[190:193], v[122:125]
	v_mfma_f32_16x16x32_bf16 v[114:117], v[158:161], v[198:201], v[114:117]
	v_mfma_f32_16x16x32_bf16 v[106:109], v[158:161], v[206:209], v[106:109]
	v_mfma_f32_16x16x32_bf16 v[98:101], v[158:161], v[214:217], v[98:101]
	v_mfma_f32_16x16x32_bf16 v[126:129], v[134:137], v[194:197], v[126:129]
	v_mfma_f32_16x16x32_bf16 v[118:121], v[134:137], v[202:205], v[118:121]
	v_mfma_f32_16x16x32_bf16 v[110:113], v[134:137], v[210:213], v[110:113]
	v_mfma_f32_16x16x32_bf16 v[102:105], v[134:137], v[218:221], v[102:105]
	v_mfma_f32_16x16x32_bf16 v[122:125], v[170:173], v[194:197], v[122:125]
	v_mfma_f32_16x16x32_bf16 v[114:117], v[170:173], v[202:205], v[114:117]
	v_mfma_f32_16x16x32_bf16 v[106:109], v[170:173], v[210:213], v[106:109]
	v_mfma_f32_16x16x32_bf16 v[98:101], v[170:173], v[218:221], v[98:101]
	s_setprio 0
	s_setprio 1
	v_mfma_f32_16x16x32_bf16 v[62:65], v[174:177], v[190:193], v[62:65]
	v_mfma_f32_16x16x32_bf16 v[54:57], v[174:177], v[198:201], v[54:57]
	v_mfma_f32_16x16x32_bf16 v[46:49], v[174:177], v[206:209], v[46:49]
	v_mfma_f32_16x16x32_bf16 v[38:41], v[174:177], v[214:217], v[38:41]
	v_mfma_f32_16x16x32_bf16 v[58:61], v[182:185], v[190:193], v[58:61]
	v_mfma_f32_16x16x32_bf16 v[50:53], v[182:185], v[198:201], v[50:53]
	v_mfma_f32_16x16x32_bf16 v[42:45], v[182:185], v[206:209], v[42:45]
	v_mfma_f32_16x16x32_bf16 v[34:37], v[182:185], v[214:217], v[34:37]
	v_mfma_f32_16x16x32_bf16 v[62:65], v[178:181], v[194:197], v[62:65]
	v_mfma_f32_16x16x32_bf16 v[54:57], v[178:181], v[202:205], v[54:57]
	v_mfma_f32_16x16x32_bf16 v[46:49], v[178:181], v[210:213], v[46:49]
	v_mfma_f32_16x16x32_bf16 v[38:41], v[178:181], v[218:221], v[38:41]
	v_mfma_f32_16x16x32_bf16 v[58:61], v[186:189], v[194:197], v[58:61]
	v_mfma_f32_16x16x32_bf16 v[50:53], v[186:189], v[202:205], v[50:53]
	v_mfma_f32_16x16x32_bf16 v[42:45], v[186:189], v[210:213], v[42:45]
	v_mfma_f32_16x16x32_bf16 v[34:37], v[186:189], v[218:221], v[34:37]
	s_setprio 0
	s_barrier
	s_add_i32 s46, s62, s22
	s_mov_b32 m0, s46
	ds_read_b128 v[190:193], v168 offset:16384
	ds_read_b128 v[194:197], v168 offset:17408
	ds_read_b128 v[198:201], v168 offset:18432
	ds_read_b128 v[202:205], v168 offset:19456
	ds_read_b128 v[206:209], v168 offset:20480
	ds_read_b128 v[210:213], v168 offset:21504
	ds_read_b128 v[214:217], v168 offset:22528
	ds_read_b128 v[218:221], v168 offset:23552
	global_load_lds_dwordx4 v142, s[14:15]
	s_add_i32 m0, s46, 0x2000
	s_add_u32 s46, s14, 0x4000
	s_addc_u32 s47, s15, 0
	s_add_i32 s48, s35, s22
	global_load_lds_dwordx4 v138, s[14:15]
	s_mov_b32 m0, s48
	s_nop 0
	global_load_lds_dwordx4 v142, s[46:47]
	s_add_i32 m0, s48, 0x2000
	s_nop 0
	global_load_lds_dwordx4 v138, s[46:47]
	s_waitcnt vmcnt(6)
	s_waitcnt lgkmcnt(0)
	s_barrier
	s_setprio 1
	s_waitcnt lgkmcnt(0)
	v_mfma_f32_16x16x32_bf16 v[94:97], v[130:133], v[190:193], v[94:97]
	v_mfma_f32_16x16x32_bf16 v[86:89], v[130:133], v[198:201], v[86:89]
	v_mfma_f32_16x16x32_bf16 v[78:81], v[130:133], v[206:209], v[78:81]
	v_mfma_f32_16x16x32_bf16 v[70:73], v[130:133], v[214:217], v[70:73]
	v_mfma_f32_16x16x32_bf16 v[90:93], v[158:161], v[190:193], v[90:93]
	v_mfma_f32_16x16x32_bf16 v[82:85], v[158:161], v[198:201], v[82:85]
	v_mfma_f32_16x16x32_bf16 v[74:77], v[158:161], v[206:209], v[74:77]
	v_mfma_f32_16x16x32_bf16 v[66:69], v[158:161], v[214:217], v[66:69]
	v_mfma_f32_16x16x32_bf16 v[94:97], v[134:137], v[194:197], v[94:97]
	v_mfma_f32_16x16x32_bf16 v[86:89], v[134:137], v[202:205], v[86:89]
	v_mfma_f32_16x16x32_bf16 v[78:81], v[134:137], v[210:213], v[78:81]
	v_mfma_f32_16x16x32_bf16 v[70:73], v[134:137], v[218:221], v[70:73]
	v_mfma_f32_16x16x32_bf16 v[90:93], v[170:173], v[194:197], v[90:93]
	v_mfma_f32_16x16x32_bf16 v[82:85], v[170:173], v[202:205], v[82:85]
	v_mfma_f32_16x16x32_bf16 v[74:77], v[170:173], v[210:213], v[74:77]
	v_mfma_f32_16x16x32_bf16 v[66:69], v[170:173], v[218:221], v[66:69]
	s_setprio 0
	s_setprio 1
	v_mfma_f32_16x16x32_bf16 v[30:33], v[174:177], v[190:193], v[30:33]
	v_mfma_f32_16x16x32_bf16 v[22:25], v[174:177], v[198:201], v[22:25]
	v_mfma_f32_16x16x32_bf16 v[14:17], v[174:177], v[206:209], v[14:17]
	v_mfma_f32_16x16x32_bf16 v[6:9], v[174:177], v[214:217], v[6:9]
	v_mfma_f32_16x16x32_bf16 v[26:29], v[182:185], v[190:193], v[26:29]
	v_mfma_f32_16x16x32_bf16 v[18:21], v[182:185], v[198:201], v[18:21]
	v_mfma_f32_16x16x32_bf16 v[10:13], v[182:185], v[206:209], v[10:13]
	v_mfma_f32_16x16x32_bf16 v[2:5], v[182:185], v[214:217], v[2:5]
	v_mfma_f32_16x16x32_bf16 v[30:33], v[178:181], v[194:197], v[30:33]
	v_mfma_f32_16x16x32_bf16 v[22:25], v[178:181], v[202:205], v[22:25]
	v_mfma_f32_16x16x32_bf16 v[14:17], v[178:181], v[210:213], v[14:17]
	v_mfma_f32_16x16x32_bf16 v[6:9], v[178:181], v[218:221], v[6:9]
	v_mfma_f32_16x16x32_bf16 v[26:29], v[186:189], v[194:197], v[26:29]
	v_mfma_f32_16x16x32_bf16 v[18:21], v[186:189], v[202:205], v[18:21]
	v_mfma_f32_16x16x32_bf16 v[10:13], v[186:189], v[210:213], v[10:13]
	v_mfma_f32_16x16x32_bf16 v[2:5], v[186:189], v[218:221], v[2:5]
	s_setprio 0
	s_barrier
; #define PG8_STAGE(bufoff, gbase, voff) do { _Pragma("unroll") for (int _i = 0; _i < 2; ++_i) \
;         __builtin_amdgcn_global_load_lds((const unsigned*)((const char*)(gbase) + (voff)[_i]), (LAS unsigned*)(lds + (bufoff) + ldsw + _i * 8192), 16, 0, 0); } while (0)
; #define PG8_LDA(dst, b, h) do { _Pragma("unroll") for (int m = 0; m < 4; ++m) _Pragma("unroll") for (int k = 0; k < 2; ++k) dst[m][k] = *(const LAS bf16x8*)(lds + PG8_SA(b, h) + aoff + m * 2048 + k * 1024); } while (0)
; #define PG8_LDB(dst, b, h) do { _Pragma("unroll") for (int n = 0; n < 2; ++n) _Pragma("unroll") for (int k = 0; k < 2; ++k) dst[n][k] = *(const LAS bf16x8*)(lds + PG8_SB(b, h) + boff + n * 2048 + k * 1024); } while (0)
; #define PG8_WAIT_V(n) asm volatile("s_waitcnt vmcnt(" #n ")" ::: "memory")
; #define PG8_WAIT_L(n) asm volatile("s_waitcnt lgkmcnt(" #n ")" ::: "memory")
; #define PG8_BAR __builtin_amdgcn_s_barrier()
; #define PG8_SCHED __builtin_amdgcn_sched_barrier(0)
; template <class Epi, class Sched, bool I8 = false>
; __device__ __forceinline__ void gemm_phase(LAS unsigned char* lds, const Gemm g, const Sched& S, const Epi& E) {
;     ...
;             PG8_LDB(B0, 1, 0); PG8_LDB(B1, 1, 1); PG8_SCHED; PG8_LDA(At, 1, 0); PG8_STAGE(PG8_SA(0, 1), a2 + hstepA, voffA);
;             PG8_WAIT_V(8); PG8_WAIT_L(0); PG8_BAR; PG8_MMA(0, 0, At, B0); PG8_MMA(0, 1, At, B1); PG8_BAR; PG8_SCHED;
;             PG8_LDA(At, 1, 1); PG8_STAGE(PG8_SB(1, 0), b3, voffB); PG8_STAGE(PG8_SB(1, 1), b3 + hstepB, voffB); PG8_STAGE(PG8_SA(1, 0), a3, voffA);
;             PG8_WAIT_V(8); PG8_WAIT_L(0); PG8_BAR; PG8_MMA(1, 0, At, B0); PG8_MMA(1, 1, At, B1); PG8_BAR; PG8_SCHED;
;         }
;         if (wr == 0) PG8_BAR;
	s_add_i32 s46, 0, 0x18000
	v_add_u32_e32 v155, s46, v165
	s_add_i32 s47, 0, 0x1c000
	ds_read_b128 v[130:133], v155
	ds_read_b128 v[134:137], v155 offset:1024
	ds_read_b128 v[158:161], v155 offset:2048
	ds_read_b128 v[170:173], v155 offset:3072
	v_add_u32_e32 v155, s47, v165
	ds_read_b128 v[174:177], v155
	ds_read_b128 v[178:181], v155 offset:1024
	ds_read_b128 v[182:185], v155 offset:2048
	ds_read_b128 v[186:189], v155 offset:3072
	s_mov_b32 m0, s26
	s_nop 0
	global_load_lds_dwordx4 v144, s[16:17]
	s_mov_b32 m0, s27
	s_nop 0
	global_load_lds_dwordx4 v140, s[16:17]
	s_add_u32 s16, s16, 0x4000
	s_addc_u32 s17, s17, 0
	s_mov_b32 m0, s28
	ds_read_b128 v[190:193], v168 offset:32768
	ds_read_b128 v[194:197], v168 offset:33792
	ds_read_b128 v[198:201], v168 offset:34816
	ds_read_b128 v[202:205], v168 offset:35840
	ds_read_b128 v[206:209], v168 offset:36864
	ds_read_b128 v[210:213], v168 offset:37888
	ds_read_b128 v[214:217], v168 offset:38912
	ds_read_b128 v[218:221], v168 offset:39936
	global_load_lds_dwordx4 v144, s[16:17]
	s_mov_b32 m0, s29
	s_nop 0
	global_load_lds_dwordx4 v140, s[16:17]
	s_waitcnt vmcnt(8)
	s_waitcnt lgkmcnt(0)
	s_barrier
	s_setprio 1
	s_waitcnt lgkmcnt(0)
	v_mfma_f32_16x16x32_bf16 v[126:129], v[130:133], v[190:193], v[126:129]
	v_mfma_f32_16x16x32_bf16 v[118:121], v[130:133], v[198:201], v[118:121]
	v_mfma_f32_16x16x32_bf16 v[110:113], v[130:133], v[206:209], v[110:113]
	v_mfma_f32_16x16x32_bf16 v[102:105], v[130:133], v[214:217], v[102:105]
	v_mfma_f32_16x16x32_bf16 v[122:125], v[158:161], v[190:193], v[122:125]
	v_mfma_f32_16x16x32_bf16 v[114:117], v[158:161], v[198:201], v[114:117]
	v_mfma_f32_16x16x32_bf16 v[106:109], v[158:161], v[206:209], v[106:109]
	v_mfma_f32_16x16x32_bf16 v[98:101], v[158:161], v[214:217], v[98:101]
	v_mfma_f32_16x16x32_bf16 v[126:129], v[134:137], v[194:197], v[126:129]
	v_mfma_f32_16x16x32_bf16 v[118:121], v[134:137], v[202:205], v[118:121]
	v_mfma_f32_16x16x32_bf16 v[110:113], v[134:137], v[210:213], v[110:113]
	v_mfma_f32_16x16x32_bf16 v[102:105], v[134:137], v[218:221], v[102:105]
	v_mfma_f32_16x16x32_bf16 v[122:125], v[170:173], v[194:197], v[122:125]
	v_mfma_f32_16x16x32_bf16 v[114:117], v[170:173], v[202:205], v[114:117]
	v_mfma_f32_16x16x32_bf16 v[106:109], v[170:173], v[210:213], v[106:109]
	v_mfma_f32_16x16x32_bf16 v[98:101], v[170:173], v[218:221], v[98:101]
	s_setprio 0
	s_setprio 1
	v_mfma_f32_16x16x32_bf16 v[62:65], v[174:177], v[190:193], v[62:65]
	v_mfma_f32_16x16x32_bf16 v[54:57], v[174:177], v[198:201], v[54:57]
	v_mfma_f32_16x16x32_bf16 v[46:49], v[174:177], v[206:209], v[46:49]
	v_mfma_f32_16x16x32_bf16 v[38:41], v[174:177], v[214:217], v[38:41]
	v_mfma_f32_16x16x32_bf16 v[58:61], v[182:185], v[190:193], v[58:61]
	v_mfma_f32_16x16x32_bf16 v[50:53], v[182:185], v[198:201], v[50:53]
	v_mfma_f32_16x16x32_bf16 v[42:45], v[182:185], v[206:209], v[42:45]
	v_mfma_f32_16x16x32_bf16 v[34:37], v[182:185], v[214:217], v[34:37]
	v_mfma_f32_16x16x32_bf16 v[62:65], v[178:181], v[194:197], v[62:65]
	v_mfma_f32_16x16x32_bf16 v[54:57], v[178:181], v[202:205], v[54:57]
	v_mfma_f32_16x16x32_bf16 v[46:49], v[178:181], v[210:213], v[46:49]
	v_mfma_f32_16x16x32_bf16 v[38:41], v[178:181], v[218:221], v[38:41]
	v_mfma_f32_16x16x32_bf16 v[58:61], v[186:189], v[194:197], v[58:61]
	v_mfma_f32_16x16x32_bf16 v[50:53], v[186:189], v[202:205], v[50:53]
	v_mfma_f32_16x16x32_bf16 v[42:45], v[186:189], v[210:213], v[42:45]
	v_mfma_f32_16x16x32_bf16 v[34:37], v[186:189], v[218:221], v[34:37]
	s_setprio 0
	s_barrier
	s_add_u32 s16, s14, 0x8000
	s_addc_u32 s17, s15, 0
	s_add_i32 s46, s46, s22
	s_mov_b32 m0, s46
	ds_read_b128 v[190:193], v168 offset:49152
	ds_read_b128 v[194:197], v168 offset:50176
	ds_read_b128 v[198:201], v168 offset:51200
	ds_read_b128 v[202:205], v168 offset:52224
	ds_read_b128 v[206:209], v168 offset:53248
	ds_read_b128 v[210:213], v168 offset:54272
	ds_read_b128 v[214:217], v168 offset:55296
	ds_read_b128 v[218:221], v168 offset:56320
	global_load_lds_dwordx4 v142, s[16:17]
	s_add_i32 m0, s46, 0x2000
	s_add_u32 s14, s14, 0xc000
	v_lshl_add_u64 v[162:163], s[16:17], 0, v[138:139]
	s_addc_u32 s15, s15, 0
	s_add_i32 s16, s47, s22
	global_load_lds_dwordx4 v[162:163], off
	s_mov_b32 m0, s16
	s_nop 0
	global_load_lds_dwordx4 v142, s[14:15]
	s_add_i32 m0, s16, 0x2000
	s_nop 0
	global_load_lds_dwordx4 v138, s[14:15]
	s_waitcnt vmcnt(6)
	s_waitcnt lgkmcnt(0)
	s_barrier
	s_setprio 1
	s_waitcnt lgkmcnt(0)
	v_mfma_f32_16x16x32_bf16 v[94:97], v[130:133], v[190:193], v[94:97]
	v_mfma_f32_16x16x32_bf16 v[86:89], v[130:133], v[198:201], v[86:89]
	v_mfma_f32_16x16x32_bf16 v[78:81], v[130:133], v[206:209], v[78:81]
	v_mfma_f32_16x16x32_bf16 v[70:73], v[130:133], v[214:217], v[70:73]
	v_mfma_f32_16x16x32_bf16 v[90:93], v[158:161], v[190:193], v[90:93]
	v_mfma_f32_16x16x32_bf16 v[82:85], v[158:161], v[198:201], v[82:85]
	v_mfma_f32_16x16x32_bf16 v[74:77], v[158:161], v[206:209], v[74:77]
	v_mfma_f32_16x16x32_bf16 v[66:69], v[158:161], v[214:217], v[66:69]
	v_mfma_f32_16x16x32_bf16 v[94:97], v[134:137], v[194:197], v[94:97]
	v_mfma_f32_16x16x32_bf16 v[86:89], v[134:137], v[202:205], v[86:89]
	v_mfma_f32_16x16x32_bf16 v[78:81], v[134:137], v[210:213], v[78:81]
	v_mfma_f32_16x16x32_bf16 v[70:73], v[134:137], v[218:221], v[70:73]
	v_mfma_f32_16x16x32_bf16 v[90:93], v[170:173], v[194:197], v[90:93]
	v_mfma_f32_16x16x32_bf16 v[82:85], v[170:173], v[202:205], v[82:85]
	v_mfma_f32_16x16x32_bf16 v[74:77], v[170:173], v[210:213], v[74:77]
	v_mfma_f32_16x16x32_bf16 v[66:69], v[170:173], v[218:221], v[66:69]
	s_setprio 0
	s_setprio 1
	v_mfma_f32_16x16x32_bf16 v[30:33], v[174:177], v[190:193], v[30:33]
	v_mfma_f32_16x16x32_bf16 v[22:25], v[174:177], v[198:201], v[22:25]
	v_mfma_f32_16x16x32_bf16 v[14:17], v[174:177], v[206:209], v[14:17]
	v_mfma_f32_16x16x32_bf16 v[6:9], v[174:177], v[214:217], v[6:9]
	v_mfma_f32_16x16x32_bf16 v[26:29], v[182:185], v[190:193], v[26:29]
	v_mfma_f32_16x16x32_bf16 v[18:21], v[182:185], v[198:201], v[18:21]
	v_mfma_f32_16x16x32_bf16 v[10:13], v[182:185], v[206:209], v[10:13]
	v_mfma_f32_16x16x32_bf16 v[2:5], v[182:185], v[214:217], v[2:5]
	v_mfma_f32_16x16x32_bf16 v[30:33], v[178:181], v[194:197], v[30:33]
	v_mfma_f32_16x16x32_bf16 v[22:25], v[178:181], v[202:205], v[22:25]
	v_mfma_f32_16x16x32_bf16 v[14:17], v[178:181], v[210:213], v[14:17]
	v_mfma_f32_16x16x32_bf16 v[6:9], v[178:181], v[218:221], v[6:9]
	v_mfma_f32_16x16x32_bf16 v[26:29], v[186:189], v[194:197], v[26:29]
	v_mfma_f32_16x16x32_bf16 v[18:21], v[186:189], v[202:205], v[18:21]
	v_mfma_f32_16x16x32_bf16 v[10:13], v[186:189], v[210:213], v[10:13]
	v_mfma_f32_16x16x32_bf16 v[2:5], v[186:189], v[218:221], v[2:5]
	s_setprio 0
	s_barrier
	s_add_i32 s45, s45, 2
	s_add_u32 s10, s10, 0x10000
	s_addc_u32 s11, s11, 0
	s_add_u32 s43, s43, 0x10000
	s_addc_u32 s44, s44, 0
	s_cmp_gt_u32 s45, 5
	s_cbranch_scc0 .LBB0_2685
	s_and_b64 vcc, exec, s[6:7]
	s_cbranch_vccz .LBB0_2688
	s_barrier

; #define PG8_STAGE(bufoff, gbase, voff) do { _Pragma("unroll") for (int _i = 0; _i < 2; ++_i) \
;         __builtin_amdgcn_global_load_lds((const unsigned*)((const char*)(gbase) + (voff)[_i]), (LAS unsigned*)(lds + (bufoff) + ldsw + _i * 8192), 16, 0, 0); } while (0)
; #define PG8_LDA(dst, b, h) do { _Pragma("unroll") for (int m = 0; m < 4; ++m) _Pragma("unroll") for (int k = 0; k < 2; ++k) dst[m][k] = *(const LAS bf16x8*)(lds + PG8_SA(b, h) + aoff + m * 2048 + k * 1024); } while (0)
; #define PG8_LDB(dst, b, h) do { _Pragma("unroll") for (int n = 0; n < 2; ++n) _Pragma("unroll") for (int k = 0; k < 2; ++k) dst[n][k] = *(const LAS bf16x8*)(lds + PG8_SB(b, h) + boff + n * 2048 + k * 1024); } while (0)
; #define PG8_WAIT_V(n) asm volatile("s_waitcnt vmcnt(" #n ")" ::: "memory")
; #define PG8_WAIT_L(n) asm volatile("s_waitcnt lgkmcnt(" #n ")" ::: "memory")
; #define PG8_BAR __builtin_amdgcn_s_barrier()
; #define PG8_SCHED __builtin_amdgcn_sched_barrier(0)
; template <class Epi, class Sched, bool I8 = false>
; __device__ __forceinline__ void gemm_phase(LAS unsigned char* lds, const Gemm g, const Sched& S, const Epi& E) {
;     ...
;         for (int t = 0; t < nt; t += 2) {
;             const bool last = (t == nt - 2);
;             const char* a1 = cA + (size_t)(t + 1) * kstep;
;             const char* a2 = last ? nA : cA + (size_t)(t + 2) * kstep; const char* b2 = last ? nB : cB + (size_t)(t + 2) * kstep;
;             const char* a3 = a2 + kstep; const char* b3 = b2 + kstep;
;             PG8_LDB(B0, 0, 0); PG8_LDB(B1, 0, 1); PG8_SCHED; PG8_LDA(At, 0, 0); PG8_STAGE(PG8_SA(1, 1), a1 + hstepA, voffA);
;             PG8_WAIT_V(8); PG8_WAIT_L(0); PG8_BAR; PG8_MMA(0, 0, At, B0); PG8_MMA(0, 1, At, B1); PG8_BAR; PG8_SCHED;
;             PG8_LDA(At, 0, 1); PG8_STAGE(PG8_SB(0, 0), b2, voffB); PG8_STAGE(PG8_SB(0, 1), b2 + hstepB, voffB); PG8_STAGE(PG8_SA(0, 0), a2, voffA);
;             PG8_WAIT_V(8); PG8_WAIT_L(0); PG8_BAR; PG8_MMA(1, 0, At, B0); PG8_MMA(1, 1, At, B1); PG8_BAR; PG8_SCHED;
.LBB0_3744:
	ds_read_b128 v[130:133], v231
	ds_read_b128 v[134:137], v231 offset:1024
	ds_read_b128 v[138:141], v231 offset:2048
	ds_read_b128 v[142:145], v231 offset:3072
	ds_read_b128 v[146:149], v232
	ds_read_b128 v[150:153], v232 offset:1024
	ds_read_b128 v[154:157], v232 offset:2048
	ds_read_b128 v[158:161], v232 offset:3072
	s_add_u32 s34, s30, 0x4000
	s_addc_u32 s35, s31, 0
	s_cmp_eq_u32 s59, 60
	s_cselect_b32 s38, s23, s34
	s_cselect_b32 s39, s5, s35
	s_cselect_b32 s36, s29, s57
	s_cselect_b32 s37, s21, s58
	s_add_u32 s34, s38, 0x8000
	s_addc_u32 s35, s39, 0
	s_sub_u32 s98, s30, 0x4000
	s_subb_u32 s99, s31, 0
	s_mov_b32 m0, s51
	s_nop 0
	global_load_lds_dwordx4 v194, s[98:99]
	s_mov_b32 m0, s52
	s_nop 0
	global_load_lds_dwordx4 v198, s[98:99]
	s_add_i32 m0, s44, 0xc000
	ds_read_b128 v[162:165], v233
	ds_read_b128 v[166:169], v233 offset:1024
	ds_read_b128 v[170:173], v233 offset:2048
	ds_read_b128 v[174:177], v233 offset:3072
	ds_read_b128 v[178:181], v233 offset:4096
	ds_read_b128 v[182:185], v233 offset:5120
	ds_read_b128 v[186:189], v233 offset:6144
	ds_read_b128 v[190:193], v233 offset:7168
	global_load_lds_dwordx4 v204, s[30:31]
	s_add_i32 m0, s44, 0xe000
	s_nop 0
	global_load_lds_dwordx4 v206, s[30:31]
	s_waitcnt vmcnt(8)
	s_waitcnt lgkmcnt(0)
	s_barrier
	s_setprio 1
	s_waitcnt lgkmcnt(0)
	v_mfma_f32_16x16x32_bf16 v[126:129], v[130:133], v[162:165], v[126:129]
	v_mfma_f32_16x16x32_bf16 v[118:121], v[130:133], v[170:173], v[118:121]
	v_mfma_f32_16x16x32_bf16 v[102:105], v[130:133], v[178:181], v[102:105]
	v_mfma_f32_16x16x32_bf16 v[86:89], v[130:133], v[186:189], v[86:89]
	v_mfma_f32_16x16x32_bf16 v[122:125], v[138:141], v[162:165], v[122:125]
	v_mfma_f32_16x16x32_bf16 v[110:113], v[138:141], v[170:173], v[110:113]
	v_mfma_f32_16x16x32_bf16 v[94:97], v[138:141], v[178:181], v[94:97]
	v_mfma_f32_16x16x32_bf16 v[78:81], v[138:141], v[186:189], v[78:81]
	v_mfma_f32_16x16x32_bf16 v[126:129], v[134:137], v[166:169], v[126:129]
	v_mfma_f32_16x16x32_bf16 v[118:121], v[134:137], v[174:177], v[118:121]
	v_mfma_f32_16x16x32_bf16 v[102:105], v[134:137], v[182:185], v[102:105]
	v_mfma_f32_16x16x32_bf16 v[86:89], v[134:137], v[190:193], v[86:89]
	v_mfma_f32_16x16x32_bf16 v[122:125], v[142:145], v[166:169], v[122:125]
	v_mfma_f32_16x16x32_bf16 v[110:113], v[142:145], v[174:177], v[110:113]
	v_mfma_f32_16x16x32_bf16 v[94:97], v[142:145], v[182:185], v[94:97]
	v_mfma_f32_16x16x32_bf16 v[78:81], v[142:145], v[190:193], v[78:81]
	s_setprio 0
	s_setprio 1
	v_mfma_f32_16x16x32_bf16 v[114:117], v[146:149], v[162:165], v[114:117]
	v_mfma_f32_16x16x32_bf16 v[98:101], v[146:149], v[170:173], v[98:101]
	v_mfma_f32_16x16x32_bf16 v[82:85], v[146:149], v[178:181], v[82:85]
	v_mfma_f32_16x16x32_bf16 v[70:73], v[146:149], v[186:189], v[70:73]
	v_mfma_f32_16x16x32_bf16 v[106:109], v[154:157], v[162:165], v[106:109]
	v_mfma_f32_16x16x32_bf16 v[90:93], v[154:157], v[170:173], v[90:93]
	v_mfma_f32_16x16x32_bf16 v[74:77], v[154:157], v[178:181], v[74:77]
	v_mfma_f32_16x16x32_bf16 v[66:69], v[154:157], v[186:189], v[66:69]
	v_mfma_f32_16x16x32_bf16 v[114:117], v[150:153], v[166:169], v[114:117]
	v_mfma_f32_16x16x32_bf16 v[98:101], v[150:153], v[174:177], v[98:101]
	v_mfma_f32_16x16x32_bf16 v[82:85], v[150:153], v[182:185], v[82:85]
	v_mfma_f32_16x16x32_bf16 v[70:73], v[150:153], v[190:193], v[70:73]
	v_mfma_f32_16x16x32_bf16 v[106:109], v[158:161], v[166:169], v[106:109]
	v_mfma_f32_16x16x32_bf16 v[90:93], v[158:161], v[174:177], v[90:93]
	v_mfma_f32_16x16x32_bf16 v[74:77], v[158:161], v[182:185], v[74:77]
	v_mfma_f32_16x16x32_bf16 v[66:69], v[158:161], v[190:193], v[66:69]
	s_setprio 0
	s_barrier
	s_add_i32 s60, s55, s43
	s_mov_b32 m0, s60
	ds_read_b128 v[162:165], v233 offset:16384
	ds_read_b128 v[166:169], v233 offset:17408
	ds_read_b128 v[170:173], v233 offset:18432
	ds_read_b128 v[174:177], v233 offset:19456
	ds_read_b128 v[178:181], v233 offset:20480
	ds_read_b128 v[182:185], v233 offset:21504
	ds_read_b128 v[186:189], v233 offset:22528
	ds_read_b128 v[190:193], v233 offset:23552
	global_load_lds_dwordx4 v196, s[36:37]
	s_add_i32 m0, s60, 0x2000
	s_add_u32 s60, s36, 0x4000
	s_addc_u32 s61, s37, 0
	s_add_i32 s62, s56, s43
	global_load_lds_dwordx4 v200, s[36:37]
	s_mov_b32 m0, s62
	s_nop 0
	global_load_lds_dwordx4 v196, s[60:61]
	s_add_i32 m0, s62, 0x2000
	s_nop 0
	global_load_lds_dwordx4 v200, s[60:61]
	s_waitcnt vmcnt(6)
	s_waitcnt lgkmcnt(0)
	s_barrier
	s_setprio 1
	s_waitcnt lgkmcnt(0)
	v_mfma_f32_16x16x32_bf16 v[62:65], v[130:133], v[162:165], v[62:65]
	v_mfma_f32_16x16x32_bf16 v[54:57], v[130:133], v[170:173], v[54:57]
	v_mfma_f32_16x16x32_bf16 v[38:41], v[130:133], v[178:181], v[38:41]
	v_mfma_f32_16x16x32_bf16 v[22:25], v[130:133], v[186:189], v[22:25]
	v_mfma_f32_16x16x32_bf16 v[58:61], v[138:141], v[162:165], v[58:61]
	v_mfma_f32_16x16x32_bf16 v[46:49], v[138:141], v[170:173], v[46:49]
	v_mfma_f32_16x16x32_bf16 v[30:33], v[138:141], v[178:181], v[30:33]
	v_mfma_f32_16x16x32_bf16 v[14:17], v[138:141], v[186:189], v[14:17]
	v_mfma_f32_16x16x32_bf16 v[62:65], v[134:137], v[166:169], v[62:65]
	v_mfma_f32_16x16x32_bf16 v[54:57], v[134:137], v[174:177], v[54:57]
	v_mfma_f32_16x16x32_bf16 v[38:41], v[134:137], v[182:185], v[38:41]
	v_mfma_f32_16x16x32_bf16 v[22:25], v[134:137], v[190:193], v[22:25]
	v_mfma_f32_16x16x32_bf16 v[58:61], v[142:145], v[166:169], v[58:61]
	v_mfma_f32_16x16x32_bf16 v[46:49], v[142:145], v[174:177], v[46:49]
	v_mfma_f32_16x16x32_bf16 v[30:33], v[142:145], v[182:185], v[30:33]
	v_mfma_f32_16x16x32_bf16 v[14:17], v[142:145], v[190:193], v[14:17]
	s_setprio 0
	s_setprio 1
	v_mfma_f32_16x16x32_bf16 v[50:53], v[146:149], v[162:165], v[50:53]
	v_mfma_f32_16x16x32_bf16 v[34:37], v[146:149], v[170:173], v[34:37]
	v_mfma_f32_16x16x32_bf16 v[18:21], v[146:149], v[178:181], v[18:21]
	v_mfma_f32_16x16x32_bf16 v[6:9], v[146:149], v[186:189], v[6:9]
	v_mfma_f32_16x16x32_bf16 v[42:45], v[154:157], v[162:165], v[42:45]
	v_mfma_f32_16x16x32_bf16 v[26:29], v[154:157], v[170:173], v[26:29]
	v_mfma_f32_16x16x32_bf16 v[10:13], v[154:157], v[178:181], v[10:13]
	v_mfma_f32_16x16x32_bf16 v[2:5], v[154:157], v[186:189], v[2:5]
	v_mfma_f32_16x16x32_bf16 v[50:53], v[150:153], v[166:169], v[50:53]
	v_mfma_f32_16x16x32_bf16 v[34:37], v[150:153], v[174:177], v[34:37]
	v_mfma_f32_16x16x32_bf16 v[18:21], v[150:153], v[182:185], v[18:21]
	v_mfma_f32_16x16x32_bf16 v[6:9], v[150:153], v[190:193], v[6:9]
	v_mfma_f32_16x16x32_bf16 v[42:45], v[158:161], v[166:169], v[42:45]
	v_mfma_f32_16x16x32_bf16 v[26:29], v[158:161], v[174:177], v[26:29]
	v_mfma_f32_16x16x32_bf16 v[10:13], v[158:161], v[182:185], v[10:13]
	v_mfma_f32_16x16x32_bf16 v[2:5], v[158:161], v[190:193], v[2:5]
	s_setprio 0
	s_barrier
; #define PG8_STAGE(bufoff, gbase, voff) do { _Pragma("unroll") for (int _i = 0; _i < 2; ++_i) \
;         __builtin_amdgcn_global_load_lds((const unsigned*)((const char*)(gbase) + (voff)[_i]), (LAS unsigned*)(lds + (bufoff) + ldsw + _i * 8192), 16, 0, 0); } while (0)
; #define PG8_LDA(dst, b, h) do { _Pragma("unroll") for (int m = 0; m < 4; ++m) _Pragma("unroll") for (int k = 0; k < 2; ++k) dst[m][k] = *(const LAS bf16x8*)(lds + PG8_SA(b, h) + aoff + m * 2048 + k * 1024); } while (0)
; #define PG8_LDB(dst, b, h) do { _Pragma("unroll") for (int n = 0; n < 2; ++n) _Pragma("unroll") for (int k = 0; k < 2; ++k) dst[n][k] = *(const LAS bf16x8*)(lds + PG8_SB(b, h) + boff + n * 2048 + k * 1024); } while (0)
; #define PG8_WAIT_V(n) asm volatile("s_waitcnt vmcnt(" #n ")" ::: "memory")
; #define PG8_WAIT_L(n) asm volatile("s_waitcnt lgkmcnt(" #n ")" ::: "memory")
; #define PG8_BAR __builtin_amdgcn_s_barrier()
; #define PG8_SCHED __builtin_amdgcn_sched_barrier(0)
; template <class Epi, class Sched, bool I8 = false>
; __device__ __forceinline__ void gemm_phase(LAS unsigned char* lds, const Gemm g, const Sched& S, const Epi& E) {
;     ...
;             PG8_LDB(B0, 1, 0); PG8_LDB(B1, 1, 1); PG8_SCHED; PG8_LDA(At, 1, 0); PG8_STAGE(PG8_SA(0, 1), a2 + hstepA, voffA);
;             PG8_WAIT_V(8); PG8_WAIT_L(0); PG8_BAR; PG8_MMA(0, 0, At, B0); PG8_MMA(0, 1, At, B1); PG8_BAR; PG8_SCHED;
;             PG8_LDA(At, 1, 1); PG8_STAGE(PG8_SB(1, 0), b3, voffB); PG8_STAGE(PG8_SB(1, 1), b3 + hstepB, voffB); PG8_STAGE(PG8_SA(1, 0), a3, voffA);
;             PG8_WAIT_V(8); PG8_WAIT_L(0); PG8_BAR; PG8_MMA(1, 0, At, B0); PG8_MMA(1, 1, At, B1); PG8_BAR; PG8_SCHED;
;         }
;         if (wr == 0) PG8_BAR;
	s_add_i32 s60, 0, 0x18000
	s_add_i32 s61, 0, 0x1c000
	v_add_u32_e32 v142, s60, v230
	v_add_u32_e32 v158, s61, v230
	ds_read_b128 v[130:133], v142
	ds_read_b128 v[134:137], v142 offset:1024
	ds_read_b128 v[138:141], v142 offset:2048
	ds_read_b128 v[142:145], v142 offset:3072
	ds_read_b128 v[146:149], v158
	ds_read_b128 v[150:153], v158 offset:1024
	ds_read_b128 v[154:157], v158 offset:2048
	ds_read_b128 v[158:161], v158 offset:3072
	s_mov_b32 m0, s44
	s_nop 0
	global_load_lds_dwordx4 v194, s[38:39]
	s_mov_b32 m0, s45
	s_nop 0
	global_load_lds_dwordx4 v198, s[38:39]
	s_add_u32 s38, s38, 0x4000
	s_addc_u32 s39, s39, 0
	s_mov_b32 m0, s46
	ds_read_b128 v[162:165], v233 offset:32768
	ds_read_b128 v[166:169], v233 offset:33792
	ds_read_b128 v[170:173], v233 offset:34816
	ds_read_b128 v[174:177], v233 offset:35840
	ds_read_b128 v[178:181], v233 offset:36864
	ds_read_b128 v[182:185], v233 offset:37888
	ds_read_b128 v[186:189], v233 offset:38912
	ds_read_b128 v[190:193], v233 offset:39936
	global_load_lds_dwordx4 v194, s[38:39]
	s_mov_b32 m0, s47
	s_nop 0
	global_load_lds_dwordx4 v198, s[38:39]
	s_waitcnt vmcnt(8)
	s_waitcnt lgkmcnt(0)
	s_barrier
	s_setprio 1
	s_waitcnt lgkmcnt(0)
	v_mfma_f32_16x16x32_bf16 v[126:129], v[130:133], v[162:165], v[126:129]
	v_mfma_f32_16x16x32_bf16 v[118:121], v[130:133], v[170:173], v[118:121]
	v_mfma_f32_16x16x32_bf16 v[102:105], v[130:133], v[178:181], v[102:105]
	v_mfma_f32_16x16x32_bf16 v[86:89], v[130:133], v[186:189], v[86:89]
	v_mfma_f32_16x16x32_bf16 v[122:125], v[138:141], v[162:165], v[122:125]
	v_mfma_f32_16x16x32_bf16 v[110:113], v[138:141], v[170:173], v[110:113]
	v_mfma_f32_16x16x32_bf16 v[94:97], v[138:141], v[178:181], v[94:97]
	v_mfma_f32_16x16x32_bf16 v[78:81], v[138:141], v[186:189], v[78:81]
	v_mfma_f32_16x16x32_bf16 v[126:129], v[134:137], v[166:169], v[126:129]
	v_mfma_f32_16x16x32_bf16 v[118:121], v[134:137], v[174:177], v[118:121]
	v_mfma_f32_16x16x32_bf16 v[102:105], v[134:137], v[182:185], v[102:105]
	v_mfma_f32_16x16x32_bf16 v[86:89], v[134:137], v[190:193], v[86:89]
	v_mfma_f32_16x16x32_bf16 v[122:125], v[142:145], v[166:169], v[122:125]
	v_mfma_f32_16x16x32_bf16 v[110:113], v[142:145], v[174:177], v[110:113]
	v_mfma_f32_16x16x32_bf16 v[94:97], v[142:145], v[182:185], v[94:97]
	v_mfma_f32_16x16x32_bf16 v[78:81], v[142:145], v[190:193], v[78:81]
	s_setprio 0
	s_setprio 1
	v_mfma_f32_16x16x32_bf16 v[114:117], v[146:149], v[162:165], v[114:117]
	v_mfma_f32_16x16x32_bf16 v[98:101], v[146:149], v[170:173], v[98:101]
	v_mfma_f32_16x16x32_bf16 v[82:85], v[146:149], v[178:181], v[82:85]
	v_mfma_f32_16x16x32_bf16 v[70:73], v[146:149], v[186:189], v[70:73]
	v_mfma_f32_16x16x32_bf16 v[106:109], v[154:157], v[162:165], v[106:109]
	v_mfma_f32_16x16x32_bf16 v[90:93], v[154:157], v[170:173], v[90:93]
	v_mfma_f32_16x16x32_bf16 v[74:77], v[154:157], v[178:181], v[74:77]
	v_mfma_f32_16x16x32_bf16 v[66:69], v[154:157], v[186:189], v[66:69]
	v_mfma_f32_16x16x32_bf16 v[114:117], v[150:153], v[166:169], v[114:117]
	v_mfma_f32_16x16x32_bf16 v[98:101], v[150:153], v[174:177], v[98:101]
	v_mfma_f32_16x16x32_bf16 v[82:85], v[150:153], v[182:185], v[82:85]
	v_mfma_f32_16x16x32_bf16 v[70:73], v[150:153], v[190:193], v[70:73]
	v_mfma_f32_16x16x32_bf16 v[106:109], v[158:161], v[166:169], v[106:109]
	v_mfma_f32_16x16x32_bf16 v[90:93], v[158:161], v[174:177], v[90:93]
	v_mfma_f32_16x16x32_bf16 v[74:77], v[158:161], v[182:185], v[74:77]
	v_mfma_f32_16x16x32_bf16 v[66:69], v[158:161], v[190:193], v[66:69]
	s_setprio 0
	s_barrier
	s_add_u32 s38, s36, 0x8000
	s_addc_u32 s39, s37, 0
	s_add_i32 s60, s60, s43
	s_mov_b32 m0, s60
	ds_read_b128 v[162:165], v233 offset:49152
	ds_read_b128 v[166:169], v233 offset:50176
	ds_read_b128 v[170:173], v233 offset:51200
	ds_read_b128 v[174:177], v233 offset:52224
	ds_read_b128 v[178:181], v233 offset:53248
	ds_read_b128 v[182:185], v233 offset:54272
	ds_read_b128 v[186:189], v233 offset:55296
	ds_read_b128 v[190:193], v233 offset:56320
	global_load_lds_dwordx4 v196, s[38:39]
	s_add_i32 m0, s60, 0x2000
	s_add_u32 s36, s36, 0xc000
	v_lshl_add_u64 v[212:213], s[38:39], 0, v[200:201]
	s_addc_u32 s37, s37, 0
	s_add_i32 s38, s61, s43
	global_load_lds_dwordx4 v[212:213], off
	s_mov_b32 m0, s38
	s_nop 0
	global_load_lds_dwordx4 v196, s[36:37]
	s_add_i32 m0, s38, 0x2000
	s_nop 0
	global_load_lds_dwordx4 v200, s[36:37]
	s_waitcnt vmcnt(6)
	s_waitcnt lgkmcnt(0)
	s_barrier
	s_setprio 1
	s_waitcnt lgkmcnt(0)
	v_mfma_f32_16x16x32_bf16 v[62:65], v[130:133], v[162:165], v[62:65]
	v_mfma_f32_16x16x32_bf16 v[54:57], v[130:133], v[170:173], v[54:57]
	v_mfma_f32_16x16x32_bf16 v[38:41], v[130:133], v[178:181], v[38:41]
	v_mfma_f32_16x16x32_bf16 v[22:25], v[130:133], v[186:189], v[22:25]
	v_mfma_f32_16x16x32_bf16 v[58:61], v[138:141], v[162:165], v[58:61]
	v_mfma_f32_16x16x32_bf16 v[46:49], v[138:141], v[170:173], v[46:49]
	v_mfma_f32_16x16x32_bf16 v[30:33], v[138:141], v[178:181], v[30:33]
	v_mfma_f32_16x16x32_bf16 v[14:17], v[138:141], v[186:189], v[14:17]
	v_mfma_f32_16x16x32_bf16 v[62:65], v[134:137], v[166:169], v[62:65]
	v_mfma_f32_16x16x32_bf16 v[54:57], v[134:137], v[174:177], v[54:57]
	v_mfma_f32_16x16x32_bf16 v[38:41], v[134:137], v[182:185], v[38:41]
	v_mfma_f32_16x16x32_bf16 v[22:25], v[134:137], v[190:193], v[22:25]
	v_mfma_f32_16x16x32_bf16 v[58:61], v[142:145], v[166:169], v[58:61]
	v_mfma_f32_16x16x32_bf16 v[46:49], v[142:145], v[174:177], v[46:49]
	v_mfma_f32_16x16x32_bf16 v[30:33], v[142:145], v[182:185], v[30:33]
	v_mfma_f32_16x16x32_bf16 v[14:17], v[142:145], v[190:193], v[14:17]
	s_setprio 0
	s_setprio 1
	v_mfma_f32_16x16x32_bf16 v[50:53], v[146:149], v[162:165], v[50:53]
	v_mfma_f32_16x16x32_bf16 v[34:37], v[146:149], v[170:173], v[34:37]
	v_mfma_f32_16x16x32_bf16 v[18:21], v[146:149], v[178:181], v[18:21]
	v_mfma_f32_16x16x32_bf16 v[6:9], v[146:149], v[186:189], v[6:9]
	v_mfma_f32_16x16x32_bf16 v[42:45], v[154:157], v[162:165], v[42:45]
	v_mfma_f32_16x16x32_bf16 v[26:29], v[154:157], v[170:173], v[26:29]
	v_mfma_f32_16x16x32_bf16 v[10:13], v[154:157], v[178:181], v[10:13]
	v_mfma_f32_16x16x32_bf16 v[2:5], v[154:157], v[186:189], v[2:5]
	v_mfma_f32_16x16x32_bf16 v[50:53], v[150:153], v[166:169], v[50:53]
	v_mfma_f32_16x16x32_bf16 v[34:37], v[150:153], v[174:177], v[34:37]
	v_mfma_f32_16x16x32_bf16 v[18:21], v[150:153], v[182:185], v[18:21]
	v_mfma_f32_16x16x32_bf16 v[6:9], v[150:153], v[190:193], v[6:9]
	v_mfma_f32_16x16x32_bf16 v[42:45], v[158:161], v[166:169], v[42:45]
	v_mfma_f32_16x16x32_bf16 v[26:29], v[158:161], v[174:177], v[26:29]
	v_mfma_f32_16x16x32_bf16 v[10:13], v[158:161], v[182:185], v[10:13]
	v_mfma_f32_16x16x32_bf16 v[2:5], v[158:161], v[190:193], v[2:5]
	s_setprio 0
	s_barrier
	s_add_i32 s59, s59, 2
	s_add_u32 s30, s30, 0x10000
	s_addc_u32 s31, s31, 0
	s_add_u32 s57, s57, 0x10000
	s_addc_u32 s58, s58, 0
	s_cmp_gt_u32 s59, 61
	s_cbranch_scc0 .LBB0_3744
	s_and_b64 vcc, exec, s[6:7]
	s_cbranch_vccz .LBB0_3747
	s_barrier

; #define PG8_STAGE(bufoff, gbase, voff) do { _Pragma("unroll") for (int _i = 0; _i < 2; ++_i) \
;         __builtin_amdgcn_global_load_lds((const unsigned*)((const char*)(gbase) + (voff)[_i]), (LAS unsigned*)(lds + (bufoff) + ldsw + _i * 8192), 16, 0, 0); } while (0)
; #define PG8_LDA(dst, b, h) do { _Pragma("unroll") for (int m = 0; m < 4; ++m) _Pragma("unroll") for (int k = 0; k < 2; ++k) dst[m][k] = *(const LAS bf16x8*)(lds + PG8_SA(b, h) + aoff + m * 2048 + k * 1024); } while (0)
; #define PG8_LDB(dst, b, h) do { _Pragma("unroll") for (int n = 0; n < 2; ++n) _Pragma("unroll") for (int k = 0; k < 2; ++k) dst[n][k] = *(const LAS bf16x8*)(lds + PG8_SB(b, h) + boff + n * 2048 + k * 1024); } while (0)
; #define PG8_WAIT_V(n) asm volatile("s_waitcnt vmcnt(" #n ")" ::: "memory")
; #define PG8_WAIT_L(n) asm volatile("s_waitcnt lgkmcnt(" #n ")" ::: "memory")
; #define PG8_BAR __builtin_amdgcn_s_barrier()
; #define PG8_SCHED __builtin_amdgcn_sched_barrier(0)
; template <class Epi, class Sched, bool I8 = false>
; __device__ __forceinline__ void gemm_phase(LAS unsigned char* lds, const Gemm g, const Sched& S, const Epi& E) {
;     ...
;         for (int t = 0; t < nt; t += 2) {
;             const bool last = (t == nt - 2);
;             const char* a1 = cA + (size_t)(t + 1) * kstep;
;             const char* a2 = last ? nA : cA + (size_t)(t + 2) * kstep; const char* b2 = last ? nB : cB + (size_t)(t + 2) * kstep;
;             const char* a3 = a2 + kstep; const char* b3 = b2 + kstep;
;             PG8_LDB(B0, 0, 0); PG8_LDB(B1, 0, 1); PG8_SCHED; PG8_LDA(At, 0, 0); PG8_STAGE(PG8_SA(1, 1), a1 + hstepA, voffA);
;             PG8_WAIT_V(8); PG8_WAIT_L(0); PG8_BAR; PG8_MMA(0, 0, At, B0); PG8_MMA(0, 1, At, B1); PG8_BAR; PG8_SCHED;
;             PG8_LDA(At, 0, 1); PG8_STAGE(PG8_SB(0, 0), b2, voffB); PG8_STAGE(PG8_SB(0, 1), b2 + hstepB, voffB); PG8_STAGE(PG8_SA(0, 0), a2, voffA);
;             PG8_WAIT_V(8); PG8_WAIT_L(0); PG8_BAR; PG8_MMA(1, 0, At, B0); PG8_MMA(1, 1, At, B1); PG8_BAR; PG8_SCHED;
.LBB0_4168:
	ds_read_b128 v[66:69], v178
	ds_read_b128 v[70:73], v178 offset:1024
	ds_read_b128 v[74:77], v178 offset:2048
	ds_read_b128 v[78:81], v178 offset:3072
	ds_read_b128 v[146:149], v179
	ds_read_b128 v[150:153], v179 offset:1024
	ds_read_b128 v[172:175], v179 offset:2048
	ds_read_b128 v[182:185], v179 offset:3072
	s_add_u32 s22, s20, 0x4000
	s_addc_u32 s23, s21, 0
	s_cmpk_eq_i32 s51, 0x52
	s_cselect_b32 s26, s0, s22
	s_cselect_b32 s27, s1, s23
	s_cselect_b32 s24, s18, s49
	s_cselect_b32 s25, s19, s50
	s_add_u32 s22, s26, 0x8000
	s_addc_u32 s23, s27, 0
	s_sub_u32 s98, s20, 0x4000
	s_subb_u32 s99, s21, 0
	s_mov_b32 m0, s39
	s_nop 0
	global_load_lds_dwordx4 v154, s[98:99]
	s_mov_b32 m0, s40
	s_nop 0
	global_load_lds_dwordx4 v158, s[98:99]
	s_add_i32 m0, s34, 0xc000
	ds_read_b128 v[186:189], v180
	ds_read_b128 v[190:193], v180 offset:1024
	ds_read_b128 v[194:197], v180 offset:2048
	ds_read_b128 v[198:201], v180 offset:3072
	ds_read_b128 v[202:205], v180 offset:4096
	ds_read_b128 v[206:209], v180 offset:5120
	ds_read_b128 v[210:213], v180 offset:6144
	ds_read_b128 v[214:217], v180 offset:7168
	global_load_lds_dwordx4 v164, s[20:21]
	s_add_i32 m0, s34, 0xe000
	s_nop 0
	global_load_lds_dwordx4 v166, s[20:21]
	s_waitcnt vmcnt(8)
	s_waitcnt lgkmcnt(0)
	s_barrier
	s_setprio 1
	s_waitcnt lgkmcnt(0)
	v_mfma_i32_16x16x64_i8 v[142:145], v[66:69], v[186:189], v[142:145]
	v_mfma_i32_16x16x64_i8 v[126:129], v[66:69], v[194:197], v[126:129]
	v_mfma_i32_16x16x64_i8 v[110:113], v[66:69], v[202:205], v[110:113]
	v_mfma_i32_16x16x64_i8 v[94:97], v[66:69], v[210:213], v[94:97]
	v_mfma_i32_16x16x64_i8 v[138:141], v[74:77], v[186:189], v[138:141]
	v_mfma_i32_16x16x64_i8 v[122:125], v[74:77], v[194:197], v[122:125]
	v_mfma_i32_16x16x64_i8 v[106:109], v[74:77], v[202:205], v[106:109]
	v_mfma_i32_16x16x64_i8 v[90:93], v[74:77], v[210:213], v[90:93]
	v_mfma_i32_16x16x64_i8 v[142:145], v[70:73], v[190:193], v[142:145]
	v_mfma_i32_16x16x64_i8 v[126:129], v[70:73], v[198:201], v[126:129]
	v_mfma_i32_16x16x64_i8 v[110:113], v[70:73], v[206:209], v[110:113]
	v_mfma_i32_16x16x64_i8 v[94:97], v[70:73], v[214:217], v[94:97]
	v_mfma_i32_16x16x64_i8 v[138:141], v[78:81], v[190:193], v[138:141]
	v_mfma_i32_16x16x64_i8 v[122:125], v[78:81], v[198:201], v[122:125]
	v_mfma_i32_16x16x64_i8 v[106:109], v[78:81], v[206:209], v[106:109]
	v_mfma_i32_16x16x64_i8 v[90:93], v[78:81], v[214:217], v[90:93]
	s_setprio 0
	s_setprio 1
	v_mfma_i32_16x16x64_i8 v[134:137], v[146:149], v[186:189], v[134:137]
	v_mfma_i32_16x16x64_i8 v[118:121], v[146:149], v[194:197], v[118:121]
	v_mfma_i32_16x16x64_i8 v[102:105], v[146:149], v[202:205], v[102:105]
	v_mfma_i32_16x16x64_i8 v[86:89], v[146:149], v[210:213], v[86:89]
	v_mfma_i32_16x16x64_i8 v[130:133], v[172:175], v[186:189], v[130:133]
	v_mfma_i32_16x16x64_i8 v[114:117], v[172:175], v[194:197], v[114:117]
	v_mfma_i32_16x16x64_i8 v[98:101], v[172:175], v[202:205], v[98:101]
	v_mfma_i32_16x16x64_i8 v[82:85], v[172:175], v[210:213], v[82:85]
	v_mfma_i32_16x16x64_i8 v[134:137], v[150:153], v[190:193], v[134:137]
	v_mfma_i32_16x16x64_i8 v[118:121], v[150:153], v[198:201], v[118:121]
	v_mfma_i32_16x16x64_i8 v[102:105], v[150:153], v[206:209], v[102:105]
	v_mfma_i32_16x16x64_i8 v[86:89], v[150:153], v[214:217], v[86:89]
	v_mfma_i32_16x16x64_i8 v[130:133], v[182:185], v[190:193], v[130:133]
	v_mfma_i32_16x16x64_i8 v[114:117], v[182:185], v[198:201], v[114:117]
	v_mfma_i32_16x16x64_i8 v[98:101], v[182:185], v[206:209], v[98:101]
	v_mfma_i32_16x16x64_i8 v[82:85], v[182:185], v[214:217], v[82:85]
	s_setprio 0
	s_barrier
	s_add_i32 s52, s43, s33
	s_mov_b32 m0, s52
	ds_read_b128 v[186:189], v180 offset:16384
	ds_read_b128 v[190:193], v180 offset:17408
	ds_read_b128 v[194:197], v180 offset:18432
	ds_read_b128 v[198:201], v180 offset:19456
	ds_read_b128 v[202:205], v180 offset:20480
	ds_read_b128 v[206:209], v180 offset:21504
	ds_read_b128 v[210:213], v180 offset:22528
	ds_read_b128 v[214:217], v180 offset:23552
	global_load_lds_dwordx4 v156, s[24:25]
	s_add_i32 m0, s52, 0x2000
	s_add_u32 s52, s24, 0x4000
	s_addc_u32 s53, s25, 0
	s_add_i32 s54, s44, s33
	global_load_lds_dwordx4 v160, s[24:25]
	s_mov_b32 m0, s54
	s_nop 0
	global_load_lds_dwordx4 v156, s[52:53]
	s_add_i32 m0, s54, 0x2000
	s_nop 0
	global_load_lds_dwordx4 v160, s[52:53]
	s_waitcnt vmcnt(6)
	s_waitcnt lgkmcnt(0)
	s_barrier
	s_setprio 1
	s_waitcnt lgkmcnt(0)
	v_mfma_i32_16x16x64_i8 v[62:65], v[66:69], v[186:189], v[62:65]
	v_mfma_i32_16x16x64_i8 v[46:49], v[66:69], v[194:197], v[46:49]
	v_mfma_i32_16x16x64_i8 v[30:33], v[66:69], v[202:205], v[30:33]
	v_mfma_i32_16x16x64_i8 v[14:17], v[66:69], v[210:213], v[14:17]
	v_mfma_i32_16x16x64_i8 v[58:61], v[74:77], v[186:189], v[58:61]
	v_mfma_i32_16x16x64_i8 v[42:45], v[74:77], v[194:197], v[42:45]
	v_mfma_i32_16x16x64_i8 v[26:29], v[74:77], v[202:205], v[26:29]
	v_mfma_i32_16x16x64_i8 v[10:13], v[74:77], v[210:213], v[10:13]
	v_mfma_i32_16x16x64_i8 v[62:65], v[70:73], v[190:193], v[62:65]
	v_mfma_i32_16x16x64_i8 v[46:49], v[70:73], v[198:201], v[46:49]
	v_mfma_i32_16x16x64_i8 v[30:33], v[70:73], v[206:209], v[30:33]
	v_mfma_i32_16x16x64_i8 v[14:17], v[70:73], v[214:217], v[14:17]
	v_mfma_i32_16x16x64_i8 v[58:61], v[78:81], v[190:193], v[58:61]
	v_mfma_i32_16x16x64_i8 v[42:45], v[78:81], v[198:201], v[42:45]
	v_mfma_i32_16x16x64_i8 v[26:29], v[78:81], v[206:209], v[26:29]
	v_mfma_i32_16x16x64_i8 v[10:13], v[78:81], v[214:217], v[10:13]
	s_setprio 0
	s_setprio 1
	v_mfma_i32_16x16x64_i8 v[54:57], v[146:149], v[186:189], v[54:57]
	v_mfma_i32_16x16x64_i8 v[38:41], v[146:149], v[194:197], v[38:41]
	v_mfma_i32_16x16x64_i8 v[22:25], v[146:149], v[202:205], v[22:25]
	v_mfma_i32_16x16x64_i8 v[6:9], v[146:149], v[210:213], v[6:9]
	v_mfma_i32_16x16x64_i8 v[50:53], v[172:175], v[186:189], v[50:53]
	v_mfma_i32_16x16x64_i8 v[34:37], v[172:175], v[194:197], v[34:37]
	v_mfma_i32_16x16x64_i8 v[18:21], v[172:175], v[202:205], v[18:21]
	v_mfma_i32_16x16x64_i8 v[2:5], v[172:175], v[210:213], v[2:5]
	v_mfma_i32_16x16x64_i8 v[54:57], v[150:153], v[190:193], v[54:57]
	v_mfma_i32_16x16x64_i8 v[38:41], v[150:153], v[198:201], v[38:41]
	v_mfma_i32_16x16x64_i8 v[22:25], v[150:153], v[206:209], v[22:25]
	v_mfma_i32_16x16x64_i8 v[6:9], v[150:153], v[214:217], v[6:9]
	v_mfma_i32_16x16x64_i8 v[50:53], v[182:185], v[190:193], v[50:53]
	v_mfma_i32_16x16x64_i8 v[34:37], v[182:185], v[198:201], v[34:37]
	v_mfma_i32_16x16x64_i8 v[18:21], v[182:185], v[206:209], v[18:21]
	v_mfma_i32_16x16x64_i8 v[2:5], v[182:185], v[214:217], v[2:5]
	s_setprio 0
	s_barrier
; #define PG8_STAGE(bufoff, gbase, voff) do { _Pragma("unroll") for (int _i = 0; _i < 2; ++_i) \
;         __builtin_amdgcn_global_load_lds((const unsigned*)((const char*)(gbase) + (voff)[_i]), (LAS unsigned*)(lds + (bufoff) + ldsw + _i * 8192), 16, 0, 0); } while (0)
; #define PG8_LDA(dst, b, h) do { _Pragma("unroll") for (int m = 0; m < 4; ++m) _Pragma("unroll") for (int k = 0; k < 2; ++k) dst[m][k] = *(const LAS bf16x8*)(lds + PG8_SA(b, h) + aoff + m * 2048 + k * 1024); } while (0)
; #define PG8_LDB(dst, b, h) do { _Pragma("unroll") for (int n = 0; n < 2; ++n) _Pragma("unroll") for (int k = 0; k < 2; ++k) dst[n][k] = *(const LAS bf16x8*)(lds + PG8_SB(b, h) + boff + n * 2048 + k * 1024); } while (0)
; #define PG8_WAIT_V(n) asm volatile("s_waitcnt vmcnt(" #n ")" ::: "memory")
; #define PG8_WAIT_L(n) asm volatile("s_waitcnt lgkmcnt(" #n ")" ::: "memory")
; #define PG8_BAR __builtin_amdgcn_s_barrier()
; #define PG8_SCHED __builtin_amdgcn_sched_barrier(0)
; template <class Epi, class Sched, bool I8 = false>
; __device__ __forceinline__ void gemm_phase(LAS unsigned char* lds, const Gemm g, const Sched& S, const Epi& E) {
;     ...
;             PG8_LDB(B0, 1, 0); PG8_LDB(B1, 1, 1); PG8_SCHED; PG8_LDA(At, 1, 0); PG8_STAGE(PG8_SA(0, 1), a2 + hstepA, voffA);
;             PG8_WAIT_V(8); PG8_WAIT_L(0); PG8_BAR; PG8_MMA(0, 0, At, B0); PG8_MMA(0, 1, At, B1); PG8_BAR; PG8_SCHED;
;             PG8_LDA(At, 1, 1); PG8_STAGE(PG8_SB(1, 0), b3, voffB); PG8_STAGE(PG8_SB(1, 1), b3 + hstepB, voffB); PG8_STAGE(PG8_SA(1, 0), a3, voffA);
;             PG8_WAIT_V(8); PG8_WAIT_L(0); PG8_BAR; PG8_MMA(1, 0, At, B0); PG8_MMA(1, 1, At, B1); PG8_BAR; PG8_SCHED;
;         }
;         if (wr == 0) PG8_BAR;
	s_add_i32 s52, 0, 0x18000
	s_add_i32 s53, 0, 0x1c000
	v_add_u32_e32 v78, s52, v176
	v_add_u32_e32 v162, s53, v176
	ds_read_b128 v[66:69], v78
	ds_read_b128 v[70:73], v78 offset:1024
	ds_read_b128 v[74:77], v78 offset:2048
	ds_read_b128 v[78:81], v78 offset:3072
	ds_read_b128 v[146:149], v162
	ds_read_b128 v[150:153], v162 offset:1024
	ds_read_b128 v[172:175], v162 offset:2048
	ds_read_b128 v[182:185], v162 offset:3072
	s_mov_b32 m0, s34
	s_nop 0
	global_load_lds_dwordx4 v154, s[26:27]
	s_mov_b32 m0, s35
	s_nop 0
	global_load_lds_dwordx4 v158, s[26:27]
	s_add_u32 s26, s26, 0x4000
	s_addc_u32 s27, s27, 0
	s_mov_b32 m0, s36
	ds_read_b128 v[186:189], v180 offset:32768
	ds_read_b128 v[190:193], v180 offset:33792
	ds_read_b128 v[194:197], v180 offset:34816
	ds_read_b128 v[198:201], v180 offset:35840
	ds_read_b128 v[202:205], v180 offset:36864
	ds_read_b128 v[206:209], v180 offset:37888
	ds_read_b128 v[210:213], v180 offset:38912
	ds_read_b128 v[214:217], v180 offset:39936
	global_load_lds_dwordx4 v154, s[26:27]
	s_mov_b32 m0, s37
	s_nop 0
	global_load_lds_dwordx4 v158, s[26:27]
	s_waitcnt vmcnt(8)
	s_waitcnt lgkmcnt(0)
	s_barrier
	s_setprio 1
	s_waitcnt lgkmcnt(0)
	v_mfma_i32_16x16x64_i8 v[142:145], v[66:69], v[186:189], v[142:145]
	v_mfma_i32_16x16x64_i8 v[126:129], v[66:69], v[194:197], v[126:129]
	v_mfma_i32_16x16x64_i8 v[110:113], v[66:69], v[202:205], v[110:113]
	v_mfma_i32_16x16x64_i8 v[94:97], v[66:69], v[210:213], v[94:97]
	v_mfma_i32_16x16x64_i8 v[138:141], v[74:77], v[186:189], v[138:141]
	v_mfma_i32_16x16x64_i8 v[122:125], v[74:77], v[194:197], v[122:125]
	v_mfma_i32_16x16x64_i8 v[106:109], v[74:77], v[202:205], v[106:109]
	v_mfma_i32_16x16x64_i8 v[90:93], v[74:77], v[210:213], v[90:93]
	v_mfma_i32_16x16x64_i8 v[142:145], v[70:73], v[190:193], v[142:145]
	v_mfma_i32_16x16x64_i8 v[126:129], v[70:73], v[198:201], v[126:129]
	v_mfma_i32_16x16x64_i8 v[110:113], v[70:73], v[206:209], v[110:113]
	v_mfma_i32_16x16x64_i8 v[94:97], v[70:73], v[214:217], v[94:97]
	v_mfma_i32_16x16x64_i8 v[138:141], v[78:81], v[190:193], v[138:141]
	v_mfma_i32_16x16x64_i8 v[122:125], v[78:81], v[198:201], v[122:125]
	v_mfma_i32_16x16x64_i8 v[106:109], v[78:81], v[206:209], v[106:109]
	v_mfma_i32_16x16x64_i8 v[90:93], v[78:81], v[214:217], v[90:93]
	s_setprio 0
	s_setprio 1
	v_mfma_i32_16x16x64_i8 v[134:137], v[146:149], v[186:189], v[134:137]
	v_mfma_i32_16x16x64_i8 v[118:121], v[146:149], v[194:197], v[118:121]
	v_mfma_i32_16x16x64_i8 v[102:105], v[146:149], v[202:205], v[102:105]
	v_mfma_i32_16x16x64_i8 v[86:89], v[146:149], v[210:213], v[86:89]
	v_mfma_i32_16x16x64_i8 v[130:133], v[172:175], v[186:189], v[130:133]
	v_mfma_i32_16x16x64_i8 v[114:117], v[172:175], v[194:197], v[114:117]
	v_mfma_i32_16x16x64_i8 v[98:101], v[172:175], v[202:205], v[98:101]
	v_mfma_i32_16x16x64_i8 v[82:85], v[172:175], v[210:213], v[82:85]
	v_mfma_i32_16x16x64_i8 v[134:137], v[150:153], v[190:193], v[134:137]
	v_mfma_i32_16x16x64_i8 v[118:121], v[150:153], v[198:201], v[118:121]
	v_mfma_i32_16x16x64_i8 v[102:105], v[150:153], v[206:209], v[102:105]
	v_mfma_i32_16x16x64_i8 v[86:89], v[150:153], v[214:217], v[86:89]
	v_mfma_i32_16x16x64_i8 v[130:133], v[182:185], v[190:193], v[130:133]
	v_mfma_i32_16x16x64_i8 v[114:117], v[182:185], v[198:201], v[114:117]
	v_mfma_i32_16x16x64_i8 v[98:101], v[182:185], v[206:209], v[98:101]
	v_mfma_i32_16x16x64_i8 v[82:85], v[182:185], v[214:217], v[82:85]
	s_setprio 0
	s_barrier
	s_add_u32 s26, s24, 0x8000
	s_addc_u32 s27, s25, 0
	s_add_i32 s52, s52, s33
	s_mov_b32 m0, s52
	ds_read_b128 v[186:189], v180 offset:49152
	ds_read_b128 v[190:193], v180 offset:50176
	ds_read_b128 v[194:197], v180 offset:51200
	ds_read_b128 v[198:201], v180 offset:52224
	ds_read_b128 v[202:205], v180 offset:53248
	ds_read_b128 v[206:209], v180 offset:54272
	ds_read_b128 v[210:213], v180 offset:55296
	ds_read_b128 v[214:217], v180 offset:56320
	global_load_lds_dwordx4 v156, s[26:27]
	s_add_i32 m0, s52, 0x2000
	s_add_u32 s24, s24, 0xc000
	v_lshl_add_u64 v[218:219], s[26:27], 0, v[160:161]
	s_addc_u32 s25, s25, 0
	s_add_i32 s26, s53, s33
	global_load_lds_dwordx4 v[218:219], off
	s_mov_b32 m0, s26
	s_nop 0
	global_load_lds_dwordx4 v156, s[24:25]
	s_add_i32 m0, s26, 0x2000
	s_nop 0
	global_load_lds_dwordx4 v160, s[24:25]
	s_waitcnt vmcnt(6)
	s_waitcnt lgkmcnt(0)
	s_barrier
	s_setprio 1
	s_waitcnt lgkmcnt(0)
	v_mfma_i32_16x16x64_i8 v[62:65], v[66:69], v[186:189], v[62:65]
	v_mfma_i32_16x16x64_i8 v[46:49], v[66:69], v[194:197], v[46:49]
	v_mfma_i32_16x16x64_i8 v[30:33], v[66:69], v[202:205], v[30:33]
	v_mfma_i32_16x16x64_i8 v[14:17], v[66:69], v[210:213], v[14:17]
	v_mfma_i32_16x16x64_i8 v[58:61], v[74:77], v[186:189], v[58:61]
	v_mfma_i32_16x16x64_i8 v[42:45], v[74:77], v[194:197], v[42:45]
	v_mfma_i32_16x16x64_i8 v[26:29], v[74:77], v[202:205], v[26:29]
	v_mfma_i32_16x16x64_i8 v[10:13], v[74:77], v[210:213], v[10:13]
	v_mfma_i32_16x16x64_i8 v[62:65], v[70:73], v[190:193], v[62:65]
	v_mfma_i32_16x16x64_i8 v[46:49], v[70:73], v[198:201], v[46:49]
	v_mfma_i32_16x16x64_i8 v[30:33], v[70:73], v[206:209], v[30:33]
	v_mfma_i32_16x16x64_i8 v[14:17], v[70:73], v[214:217], v[14:17]
	v_mfma_i32_16x16x64_i8 v[58:61], v[78:81], v[190:193], v[58:61]
	v_mfma_i32_16x16x64_i8 v[42:45], v[78:81], v[198:201], v[42:45]
	v_mfma_i32_16x16x64_i8 v[26:29], v[78:81], v[206:209], v[26:29]
	v_mfma_i32_16x16x64_i8 v[10:13], v[78:81], v[214:217], v[10:13]
	s_setprio 0
	s_setprio 1
	v_mfma_i32_16x16x64_i8 v[54:57], v[146:149], v[186:189], v[54:57]
	v_mfma_i32_16x16x64_i8 v[38:41], v[146:149], v[194:197], v[38:41]
	v_mfma_i32_16x16x64_i8 v[22:25], v[146:149], v[202:205], v[22:25]
	v_mfma_i32_16x16x64_i8 v[6:9], v[146:149], v[210:213], v[6:9]
	v_mfma_i32_16x16x64_i8 v[50:53], v[172:175], v[186:189], v[50:53]
	v_mfma_i32_16x16x64_i8 v[34:37], v[172:175], v[194:197], v[34:37]
	v_mfma_i32_16x16x64_i8 v[18:21], v[172:175], v[202:205], v[18:21]
	v_mfma_i32_16x16x64_i8 v[2:5], v[172:175], v[210:213], v[2:5]
	v_mfma_i32_16x16x64_i8 v[54:57], v[150:153], v[190:193], v[54:57]
	v_mfma_i32_16x16x64_i8 v[38:41], v[150:153], v[198:201], v[38:41]
	v_mfma_i32_16x16x64_i8 v[22:25], v[150:153], v[206:209], v[22:25]
	v_mfma_i32_16x16x64_i8 v[6:9], v[150:153], v[214:217], v[6:9]
	v_mfma_i32_16x16x64_i8 v[50:53], v[182:185], v[190:193], v[50:53]
	v_mfma_i32_16x16x64_i8 v[34:37], v[182:185], v[198:201], v[34:37]
	v_mfma_i32_16x16x64_i8 v[18:21], v[182:185], v[206:209], v[18:21]
	v_mfma_i32_16x16x64_i8 v[2:5], v[182:185], v[214:217], v[2:5]
	s_setprio 0
	s_barrier
	s_add_i32 s51, s51, 2
	s_add_u32 s20, s20, 0x10000
	s_addc_u32 s21, s21, 0
	s_add_u32 s49, s49, 0x10000
	s_addc_u32 s50, s50, 0
	s_cmpk_gt_u32 s51, 0x53
	s_cbranch_scc0 .LBB0_4168
	s_and_b64 vcc, exec, s[14:15]
	s_cbranch_vccz .LBB0_4171
	s_barrier
